# hand-written branch-free in-projection epilogue for plain activation tiles (silu/gelu/sigmoid -> PROJ), same f32 arithmetic, packed f32 ops, one nrm LDS read batch, saddr stores
# speedup vs baseline: 1.0202x; 1.0175x over previous
.LBB0_123:
	s_cmp_eq_u32 s17, 0
	s_cbranch_scc1 .Lfe_slow
	s_cmp_eq_u32 s17, 2
	s_cbranch_scc0 .Lfe_fast
	s_cmp_lt_u32 s35, 12
	s_cbranch_scc1 .Lfe_fast

.LBB0_651:
	s_or_b64 exec, exec, s[0:1]
.Lfe_done:
	s_andn2_b64 vcc, exec, s[40:41]
	s_mov_b64 s[0:1], -1
	s_cbranch_vccnz .LBB0_113
.LBB0_652:
	s_andn2_b64 vcc, exec, s[4:5]
	s_cbranch_vccnz .LBB0_112
	s_barrier
	s_branch .LBB0_112
.Lfe_fast:
	s_lshl_b32 s19, s42, 8
	s_add_i32 s19, s19, s71
	v_or_b32_e32 v162, s19, v147
	v_lshl_or_b32 v130, s35, 8, v174
	s_movk_i32 s27, 0x6a00
	ds_read_b32 v176, v172
	ds_read_b32 v178, v172 offset:64
	ds_read_b32 v180, v172 offset:128
	ds_read_b32 v182, v172 offset:192
	ds_read_b32 v184, v172 offset:512
	ds_read_b32 v186, v172 offset:576
	ds_read_b32 v188, v172 offset:640
	ds_read_b32 v190, v172 offset:704
	v_mul_u32_u24_e32 v165, s27, v162
	v_readlane_b32 s34, v251, 14
	v_readlane_b32 s35, v251, 15
	v_lshl_add_u32 v165, v130, 1, v165
	s_mov_b32 s0, 1.0
	s_mov_b32 s28, 0xbfb8aa3b
	s_mov_b32 s2, 0x3d372713
	s_mov_b32 s48, 0x3fcc422a
	s_cmp_eq_u32 s17, 3
	s_waitcnt lgkmcnt(0)
	s_cbranch_scc1 .Lfe_sig
	s_cmp_eq_u32 s17, 1
	s_cbranch_scc1 .Lfe_silu
	v_pk_mul_f32 v[126:127], v[126:127], v[176:177] op_sel_hi:[1,0]
	v_pk_mul_f32 v[128:129], v[128:129], v[176:177] op_sel_hi:[1,0]
	v_pk_mul_f32 v[122:123], v[122:123], v[176:177] op_sel_hi:[1,0]
	v_pk_mul_f32 v[124:125], v[124:125], v[176:177] op_sel_hi:[1,0]
	v_pk_mul_f32 v[154:155], v[126:127], s[2:3] op_sel_hi:[1,0]
	v_pk_mul_f32 v[156:157], v[128:129], s[2:3] op_sel_hi:[1,0]
	v_pk_mul_f32 v[158:159], v[122:123], s[2:3] op_sel_hi:[1,0]
	v_pk_mul_f32 v[160:161], v[124:125], s[2:3] op_sel_hi:[1,0]
	v_pk_mul_f32 v[154:155], v[126:127], v[154:155]
	v_pk_mul_f32 v[156:157], v[128:129], v[156:157]
	v_pk_mul_f32 v[158:159], v[122:123], v[158:159]
	v_pk_mul_f32 v[160:161], v[124:125], v[160:161]
	v_pk_fma_f32 v[154:155], v[126:127], v[154:155], v[126:127]
	v_pk_fma_f32 v[156:157], v[128:129], v[156:157], v[128:129]
	v_pk_fma_f32 v[158:159], v[122:123], v[158:159], v[122:123]
	v_pk_fma_f32 v[160:161], v[124:125], v[160:161], v[124:125]
	v_pk_mul_f32 v[154:155], v[154:155], s[48:49] op_sel_hi:[1,0]
	v_pk_mul_f32 v[156:157], v[156:157], s[48:49] op_sel_hi:[1,0]
	v_pk_mul_f32 v[158:159], v[158:159], s[48:49] op_sel_hi:[1,0]
	v_pk_mul_f32 v[160:161], v[160:161], s[48:49] op_sel_hi:[1,0]
	v_pk_mul_f32 v[154:155], v[154:155], s[28:29] op_sel_hi:[1,0]
	v_pk_mul_f32 v[156:157], v[156:157], s[28:29] op_sel_hi:[1,0]
	v_pk_mul_f32 v[158:159], v[158:159], s[28:29] op_sel_hi:[1,0]
	v_pk_mul_f32 v[160:161], v[160:161], s[28:29] op_sel_hi:[1,0]
	v_exp_f32_e32 v154, v154
	v_exp_f32_e32 v155, v155
	v_exp_f32_e32 v156, v156
	v_exp_f32_e32 v157, v157
	v_exp_f32_e32 v158, v158
	v_exp_f32_e32 v159, v159
	v_exp_f32_e32 v160, v160
	v_exp_f32_e32 v161, v161
	v_pk_add_f32 v[154:155], v[154:155], s[0:1] op_sel_hi:[1,0]
	v_pk_add_f32 v[156:157], v[156:157], s[0:1] op_sel_hi:[1,0]
	v_pk_add_f32 v[158:159], v[158:159], s[0:1] op_sel_hi:[1,0]
	v_pk_add_f32 v[160:161], v[160:161], s[0:1] op_sel_hi:[1,0]
	v_rcp_f32_e32 v154, v154
	v_rcp_f32_e32 v155, v155
	v_rcp_f32_e32 v156, v156
	v_rcp_f32_e32 v157, v157
	v_rcp_f32_e32 v158, v158
	v_rcp_f32_e32 v159, v159
	v_rcp_f32_e32 v160, v160
	v_rcp_f32_e32 v161, v161
	v_pk_mul_f32 v[126:127], v[126:127], v[154:155]
	v_pk_mul_f32 v[128:129], v[128:129], v[156:157]
	v_pk_mul_f32 v[122:123], v[122:123], v[158:159]
	v_pk_mul_f32 v[124:125], v[124:125], v[160:161]
	v_cvt_pk_bf16_f32 v130, v126, v127
	v_cvt_pk_bf16_f32 v131, v128, v129
	v_cvt_pk_bf16_f32 v132, v122, v123
	v_cvt_pk_bf16_f32 v133, v124, v125
	global_store_dwordx4 v165, v[130:133], s[34:35] nt
	v_pk_mul_f32 v[118:119], v[118:119], v[176:177] op_sel_hi:[1,0]
	v_pk_mul_f32 v[120:121], v[120:121], v[176:177] op_sel_hi:[1,0]
	v_pk_mul_f32 v[114:115], v[114:115], v[176:177] op_sel_hi:[1,0]
	v_pk_mul_f32 v[116:117], v[116:117], v[176:177] op_sel_hi:[1,0]
	v_pk_mul_f32 v[154:155], v[118:119], s[2:3] op_sel_hi:[1,0]
	v_pk_mul_f32 v[156:157], v[120:121], s[2:3] op_sel_hi:[1,0]
	v_pk_mul_f32 v[158:159], v[114:115], s[2:3] op_sel_hi:[1,0]
	v_pk_mul_f32 v[160:161], v[116:117], s[2:3] op_sel_hi:[1,0]
	v_pk_mul_f32 v[154:155], v[118:119], v[154:155]
	v_pk_mul_f32 v[156:157], v[120:121], v[156:157]
	v_pk_mul_f32 v[158:159], v[114:115], v[158:159]
	v_pk_mul_f32 v[160:161], v[116:117], v[160:161]
	v_pk_fma_f32 v[154:155], v[118:119], v[154:155], v[118:119]
	v_pk_fma_f32 v[156:157], v[120:121], v[156:157], v[120:121]
	v_pk_fma_f32 v[158:159], v[114:115], v[158:159], v[114:115]
	v_pk_fma_f32 v[160:161], v[116:117], v[160:161], v[116:117]
	v_pk_mul_f32 v[154:155], v[154:155], s[48:49] op_sel_hi:[1,0]
	v_pk_mul_f32 v[156:157], v[156:157], s[48:49] op_sel_hi:[1,0]
	v_pk_mul_f32 v[158:159], v[158:159], s[48:49] op_sel_hi:[1,0]
	v_pk_mul_f32 v[160:161], v[160:161], s[48:49] op_sel_hi:[1,0]
	v_pk_mul_f32 v[154:155], v[154:155], s[28:29] op_sel_hi:[1,0]
	v_pk_mul_f32 v[156:157], v[156:157], s[28:29] op_sel_hi:[1,0]
	v_pk_mul_f32 v[158:159], v[158:159], s[28:29] op_sel_hi:[1,0]
	v_pk_mul_f32 v[160:161], v[160:161], s[28:29] op_sel_hi:[1,0]
	v_exp_f32_e32 v154, v154
	v_exp_f32_e32 v155, v155
	v_exp_f32_e32 v156, v156
	v_exp_f32_e32 v157, v157
	v_exp_f32_e32 v158, v158
	v_exp_f32_e32 v159, v159
	v_exp_f32_e32 v160, v160
	v_exp_f32_e32 v161, v161
	v_pk_add_f32 v[154:155], v[154:155], s[0:1] op_sel_hi:[1,0]
	v_pk_add_f32 v[156:157], v[156:157], s[0:1] op_sel_hi:[1,0]
	v_pk_add_f32 v[158:159], v[158:159], s[0:1] op_sel_hi:[1,0]
	v_pk_add_f32 v[160:161], v[160:161], s[0:1] op_sel_hi:[1,0]
	v_rcp_f32_e32 v154, v154
	v_rcp_f32_e32 v155, v155
	v_rcp_f32_e32 v156, v156
	v_rcp_f32_e32 v157, v157
	v_rcp_f32_e32 v158, v158
	v_rcp_f32_e32 v159, v159
	v_rcp_f32_e32 v160, v160
	v_rcp_f32_e32 v161, v161
	v_pk_mul_f32 v[118:119], v[118:119], v[154:155]
	v_pk_mul_f32 v[120:121], v[120:121], v[156:157]
	v_pk_mul_f32 v[114:115], v[114:115], v[158:159]
	v_pk_mul_f32 v[116:117], v[116:117], v[160:161]
	v_cvt_pk_bf16_f32 v134, v118, v119
	v_cvt_pk_bf16_f32 v135, v120, v121
	v_cvt_pk_bf16_f32 v136, v114, v115
	v_cvt_pk_bf16_f32 v137, v116, v117
	global_store_dwordx4 v165, v[134:137], s[34:35] offset:256 nt
	v_add_u32_e32 v166, 0x6a000, v165
	v_pk_mul_f32 v[110:111], v[110:111], v[178:179] op_sel_hi:[1,0]
	v_pk_mul_f32 v[112:113], v[112:113], v[178:179] op_sel_hi:[1,0]
	v_pk_mul_f32 v[106:107], v[106:107], v[178:179] op_sel_hi:[1,0]
	v_pk_mul_f32 v[108:109], v[108:109], v[178:179] op_sel_hi:[1,0]
	v_pk_mul_f32 v[154:155], v[110:111], s[2:3] op_sel_hi:[1,0]
	v_pk_mul_f32 v[156:157], v[112:113], s[2:3] op_sel_hi:[1,0]
	v_pk_mul_f32 v[158:159], v[106:107], s[2:3] op_sel_hi:[1,0]
	v_pk_mul_f32 v[160:161], v[108:109], s[2:3] op_sel_hi:[1,0]
	v_pk_mul_f32 v[154:155], v[110:111], v[154:155]
	v_pk_mul_f32 v[156:157], v[112:113], v[156:157]
	v_pk_mul_f32 v[158:159], v[106:107], v[158:159]
	v_pk_mul_f32 v[160:161], v[108:109], v[160:161]
	v_pk_fma_f32 v[154:155], v[110:111], v[154:155], v[110:111]
	v_pk_fma_f32 v[156:157], v[112:113], v[156:157], v[112:113]
	v_pk_fma_f32 v[158:159], v[106:107], v[158:159], v[106:107]
	v_pk_fma_f32 v[160:161], v[108:109], v[160:161], v[108:109]
	v_pk_mul_f32 v[154:155], v[154:155], s[48:49] op_sel_hi:[1,0]
	v_pk_mul_f32 v[156:157], v[156:157], s[48:49] op_sel_hi:[1,0]
	v_pk_mul_f32 v[158:159], v[158:159], s[48:49] op_sel_hi:[1,0]
	v_pk_mul_f32 v[160:161], v[160:161], s[48:49] op_sel_hi:[1,0]
	v_pk_mul_f32 v[154:155], v[154:155], s[28:29] op_sel_hi:[1,0]
	v_pk_mul_f32 v[156:157], v[156:157], s[28:29] op_sel_hi:[1,0]
	v_pk_mul_f32 v[158:159], v[158:159], s[28:29] op_sel_hi:[1,0]
	v_pk_mul_f32 v[160:161], v[160:161], s[28:29] op_sel_hi:[1,0]
	v_exp_f32_e32 v154, v154
	v_exp_f32_e32 v155, v155
	v_exp_f32_e32 v156, v156
	v_exp_f32_e32 v157, v157
	v_exp_f32_e32 v158, v158
	v_exp_f32_e32 v159, v159
	v_exp_f32_e32 v160, v160
	v_exp_f32_e32 v161, v161
	v_pk_add_f32 v[154:155], v[154:155], s[0:1] op_sel_hi:[1,0]
	v_pk_add_f32 v[156:157], v[156:157], s[0:1] op_sel_hi:[1,0]
	v_pk_add_f32 v[158:159], v[158:159], s[0:1] op_sel_hi:[1,0]
	v_pk_add_f32 v[160:161], v[160:161], s[0:1] op_sel_hi:[1,0]
	v_rcp_f32_e32 v154, v154
	v_rcp_f32_e32 v155, v155
	v_rcp_f32_e32 v156, v156
	v_rcp_f32_e32 v157, v157
	v_rcp_f32_e32 v158, v158
	v_rcp_f32_e32 v159, v159
	v_rcp_f32_e32 v160, v160
	v_rcp_f32_e32 v161, v161
	v_pk_mul_f32 v[110:111], v[110:111], v[154:155]
	v_pk_mul_f32 v[112:113], v[112:113], v[156:157]
	v_pk_mul_f32 v[106:107], v[106:107], v[158:159]
	v_pk_mul_f32 v[108:109], v[108:109], v[160:161]
	v_cvt_pk_bf16_f32 v130, v110, v111
	v_cvt_pk_bf16_f32 v131, v112, v113
	v_cvt_pk_bf16_f32 v132, v106, v107
	v_cvt_pk_bf16_f32 v133, v108, v109
	global_store_dwordx4 v166, v[130:133], s[34:35] nt
	v_pk_mul_f32 v[102:103], v[102:103], v[178:179] op_sel_hi:[1,0]
	v_pk_mul_f32 v[104:105], v[104:105], v[178:179] op_sel_hi:[1,0]
	v_pk_mul_f32 v[98:99], v[98:99], v[178:179] op_sel_hi:[1,0]
	v_pk_mul_f32 v[100:101], v[100:101], v[178:179] op_sel_hi:[1,0]
	v_pk_mul_f32 v[154:155], v[102:103], s[2:3] op_sel_hi:[1,0]
	v_pk_mul_f32 v[156:157], v[104:105], s[2:3] op_sel_hi:[1,0]
	v_pk_mul_f32 v[158:159], v[98:99], s[2:3] op_sel_hi:[1,0]
	v_pk_mul_f32 v[160:161], v[100:101], s[2:3] op_sel_hi:[1,0]
	v_pk_mul_f32 v[154:155], v[102:103], v[154:155]
	v_pk_mul_f32 v[156:157], v[104:105], v[156:157]
	v_pk_mul_f32 v[158:159], v[98:99], v[158:159]
	v_pk_mul_f32 v[160:161], v[100:101], v[160:161]
	v_pk_fma_f32 v[154:155], v[102:103], v[154:155], v[102:103]
	v_pk_fma_f32 v[156:157], v[104:105], v[156:157], v[104:105]
	v_pk_fma_f32 v[158:159], v[98:99], v[158:159], v[98:99]
	v_pk_fma_f32 v[160:161], v[100:101], v[160:161], v[100:101]
	v_pk_mul_f32 v[154:155], v[154:155], s[48:49] op_sel_hi:[1,0]
	v_pk_mul_f32 v[156:157], v[156:157], s[48:49] op_sel_hi:[1,0]
	v_pk_mul_f32 v[158:159], v[158:159], s[48:49] op_sel_hi:[1,0]
	v_pk_mul_f32 v[160:161], v[160:161], s[48:49] op_sel_hi:[1,0]
	v_pk_mul_f32 v[154:155], v[154:155], s[28:29] op_sel_hi:[1,0]
	v_pk_mul_f32 v[156:157], v[156:157], s[28:29] op_sel_hi:[1,0]
	v_pk_mul_f32 v[158:159], v[158:159], s[28:29] op_sel_hi:[1,0]
	v_pk_mul_f32 v[160:161], v[160:161], s[28:29] op_sel_hi:[1,0]
	v_exp_f32_e32 v154, v154
	v_exp_f32_e32 v155, v155
	v_exp_f32_e32 v156, v156
	v_exp_f32_e32 v157, v157
	v_exp_f32_e32 v158, v158
	v_exp_f32_e32 v159, v159
	v_exp_f32_e32 v160, v160
	v_exp_f32_e32 v161, v161
	v_pk_add_f32 v[154:155], v[154:155], s[0:1] op_sel_hi:[1,0]
	v_pk_add_f32 v[156:157], v[156:157], s[0:1] op_sel_hi:[1,0]
	v_pk_add_f32 v[158:159], v[158:159], s[0:1] op_sel_hi:[1,0]
	v_pk_add_f32 v[160:161], v[160:161], s[0:1] op_sel_hi:[1,0]
	v_rcp_f32_e32 v154, v154
	v_rcp_f32_e32 v155, v155
	v_rcp_f32_e32 v156, v156
	v_rcp_f32_e32 v157, v157
	v_rcp_f32_e32 v158, v158
	v_rcp_f32_e32 v159, v159
	v_rcp_f32_e32 v160, v160
	v_rcp_f32_e32 v161, v161
	v_pk_mul_f32 v[102:103], v[102:103], v[154:155]
	v_pk_mul_f32 v[104:105], v[104:105], v[156:157]
	v_pk_mul_f32 v[98:99], v[98:99], v[158:159]
	v_pk_mul_f32 v[100:101], v[100:101], v[160:161]
	v_cvt_pk_bf16_f32 v134, v102, v103
	v_cvt_pk_bf16_f32 v135, v104, v105
	v_cvt_pk_bf16_f32 v136, v98, v99
	v_cvt_pk_bf16_f32 v137, v100, v101
	global_store_dwordx4 v166, v[134:137], s[34:35] offset:256 nt
	v_add_u32_e32 v164, 0xd4000, v165
	v_pk_mul_f32 v[94:95], v[94:95], v[180:181] op_sel_hi:[1,0]
	v_pk_mul_f32 v[96:97], v[96:97], v[180:181] op_sel_hi:[1,0]
	v_pk_mul_f32 v[90:91], v[90:91], v[180:181] op_sel_hi:[1,0]
	v_pk_mul_f32 v[92:93], v[92:93], v[180:181] op_sel_hi:[1,0]
	v_pk_mul_f32 v[154:155], v[94:95], s[2:3] op_sel_hi:[1,0]
	v_pk_mul_f32 v[156:157], v[96:97], s[2:3] op_sel_hi:[1,0]
	v_pk_mul_f32 v[158:159], v[90:91], s[2:3] op_sel_hi:[1,0]
	v_pk_mul_f32 v[160:161], v[92:93], s[2:3] op_sel_hi:[1,0]
	v_pk_mul_f32 v[154:155], v[94:95], v[154:155]
	v_pk_mul_f32 v[156:157], v[96:97], v[156:157]
	v_pk_mul_f32 v[158:159], v[90:91], v[158:159]
	v_pk_mul_f32 v[160:161], v[92:93], v[160:161]
	v_pk_fma_f32 v[154:155], v[94:95], v[154:155], v[94:95]
	v_pk_fma_f32 v[156:157], v[96:97], v[156:157], v[96:97]
	v_pk_fma_f32 v[158:159], v[90:91], v[158:159], v[90:91]
	v_pk_fma_f32 v[160:161], v[92:93], v[160:161], v[92:93]
	v_pk_mul_f32 v[154:155], v[154:155], s[48:49] op_sel_hi:[1,0]
	v_pk_mul_f32 v[156:157], v[156:157], s[48:49] op_sel_hi:[1,0]
	v_pk_mul_f32 v[158:159], v[158:159], s[48:49] op_sel_hi:[1,0]
	v_pk_mul_f32 v[160:161], v[160:161], s[48:49] op_sel_hi:[1,0]
	v_pk_mul_f32 v[154:155], v[154:155], s[28:29] op_sel_hi:[1,0]
	v_pk_mul_f32 v[156:157], v[156:157], s[28:29] op_sel_hi:[1,0]
	v_pk_mul_f32 v[158:159], v[158:159], s[28:29] op_sel_hi:[1,0]
	v_pk_mul_f32 v[160:161], v[160:161], s[28:29] op_sel_hi:[1,0]
	v_exp_f32_e32 v154, v154
	v_exp_f32_e32 v155, v155
	v_exp_f32_e32 v156, v156
	v_exp_f32_e32 v157, v157
	v_exp_f32_e32 v158, v158
	v_exp_f32_e32 v159, v159
	v_exp_f32_e32 v160, v160
	v_exp_f32_e32 v161, v161
	v_pk_add_f32 v[154:155], v[154:155], s[0:1] op_sel_hi:[1,0]
	v_pk_add_f32 v[156:157], v[156:157], s[0:1] op_sel_hi:[1,0]
	v_pk_add_f32 v[158:159], v[158:159], s[0:1] op_sel_hi:[1,0]
	v_pk_add_f32 v[160:161], v[160:161], s[0:1] op_sel_hi:[1,0]
	v_rcp_f32_e32 v154, v154
	v_rcp_f32_e32 v155, v155
	v_rcp_f32_e32 v156, v156
	v_rcp_f32_e32 v157, v157
	v_rcp_f32_e32 v158, v158
	v_rcp_f32_e32 v159, v159
	v_rcp_f32_e32 v160, v160
	v_rcp_f32_e32 v161, v161
	v_pk_mul_f32 v[94:95], v[94:95], v[154:155]
	v_pk_mul_f32 v[96:97], v[96:97], v[156:157]
	v_pk_mul_f32 v[90:91], v[90:91], v[158:159]
	v_pk_mul_f32 v[92:93], v[92:93], v[160:161]
	v_cvt_pk_bf16_f32 v130, v94, v95
	v_cvt_pk_bf16_f32 v131, v96, v97
	v_cvt_pk_bf16_f32 v132, v90, v91
	v_cvt_pk_bf16_f32 v133, v92, v93
	global_store_dwordx4 v164, v[130:133], s[34:35] nt
	v_pk_mul_f32 v[86:87], v[86:87], v[180:181] op_sel_hi:[1,0]
	v_pk_mul_f32 v[88:89], v[88:89], v[180:181] op_sel_hi:[1,0]
	v_pk_mul_f32 v[82:83], v[82:83], v[180:181] op_sel_hi:[1,0]
	v_pk_mul_f32 v[84:85], v[84:85], v[180:181] op_sel_hi:[1,0]
	v_pk_mul_f32 v[154:155], v[86:87], s[2:3] op_sel_hi:[1,0]
	v_pk_mul_f32 v[156:157], v[88:89], s[2:3] op_sel_hi:[1,0]
	v_pk_mul_f32 v[158:159], v[82:83], s[2:3] op_sel_hi:[1,0]
	v_pk_mul_f32 v[160:161], v[84:85], s[2:3] op_sel_hi:[1,0]
	v_pk_mul_f32 v[154:155], v[86:87], v[154:155]
	v_pk_mul_f32 v[156:157], v[88:89], v[156:157]
	v_pk_mul_f32 v[158:159], v[82:83], v[158:159]
	v_pk_mul_f32 v[160:161], v[84:85], v[160:161]
	v_pk_fma_f32 v[154:155], v[86:87], v[154:155], v[86:87]
	v_pk_fma_f32 v[156:157], v[88:89], v[156:157], v[88:89]
	v_pk_fma_f32 v[158:159], v[82:83], v[158:159], v[82:83]
	v_pk_fma_f32 v[160:161], v[84:85], v[160:161], v[84:85]
	v_pk_mul_f32 v[154:155], v[154:155], s[48:49] op_sel_hi:[1,0]
	v_pk_mul_f32 v[156:157], v[156:157], s[48:49] op_sel_hi:[1,0]
	v_pk_mul_f32 v[158:159], v[158:159], s[48:49] op_sel_hi:[1,0]
	v_pk_mul_f32 v[160:161], v[160:161], s[48:49] op_sel_hi:[1,0]
	v_pk_mul_f32 v[154:155], v[154:155], s[28:29] op_sel_hi:[1,0]
	v_pk_mul_f32 v[156:157], v[156:157], s[28:29] op_sel_hi:[1,0]
	v_pk_mul_f32 v[158:159], v[158:159], s[28:29] op_sel_hi:[1,0]
	v_pk_mul_f32 v[160:161], v[160:161], s[28:29] op_sel_hi:[1,0]
	v_exp_f32_e32 v154, v154
	v_exp_f32_e32 v155, v155
	v_exp_f32_e32 v156, v156
	v_exp_f32_e32 v157, v157
	v_exp_f32_e32 v158, v158
	v_exp_f32_e32 v159, v159
	v_exp_f32_e32 v160, v160
	v_exp_f32_e32 v161, v161
	v_pk_add_f32 v[154:155], v[154:155], s[0:1] op_sel_hi:[1,0]
	v_pk_add_f32 v[156:157], v[156:157], s[0:1] op_sel_hi:[1,0]
	v_pk_add_f32 v[158:159], v[158:159], s[0:1] op_sel_hi:[1,0]
	v_pk_add_f32 v[160:161], v[160:161], s[0:1] op_sel_hi:[1,0]
	v_rcp_f32_e32 v154, v154
	v_rcp_f32_e32 v155, v155
	v_rcp_f32_e32 v156, v156
	v_rcp_f32_e32 v157, v157
	v_rcp_f32_e32 v158, v158
	v_rcp_f32_e32 v159, v159
	v_rcp_f32_e32 v160, v160
	v_rcp_f32_e32 v161, v161
	v_pk_mul_f32 v[86:87], v[86:87], v[154:155]
	v_pk_mul_f32 v[88:89], v[88:89], v[156:157]
	v_pk_mul_f32 v[82:83], v[82:83], v[158:159]
	v_pk_mul_f32 v[84:85], v[84:85], v[160:161]
	v_cvt_pk_bf16_f32 v134, v86, v87
	v_cvt_pk_bf16_f32 v135, v88, v89
	v_cvt_pk_bf16_f32 v136, v82, v83
	v_cvt_pk_bf16_f32 v137, v84, v85
	global_store_dwordx4 v164, v[134:137], s[34:35] offset:256 nt
	v_add_u32_e32 v166, 0x13e000, v165
	v_pk_mul_f32 v[78:79], v[78:79], v[182:183] op_sel_hi:[1,0]
	v_pk_mul_f32 v[80:81], v[80:81], v[182:183] op_sel_hi:[1,0]
	v_pk_mul_f32 v[74:75], v[74:75], v[182:183] op_sel_hi:[1,0]
	v_pk_mul_f32 v[76:77], v[76:77], v[182:183] op_sel_hi:[1,0]
	v_pk_mul_f32 v[154:155], v[78:79], s[2:3] op_sel_hi:[1,0]
	v_pk_mul_f32 v[156:157], v[80:81], s[2:3] op_sel_hi:[1,0]
	v_pk_mul_f32 v[158:159], v[74:75], s[2:3] op_sel_hi:[1,0]
	v_pk_mul_f32 v[160:161], v[76:77], s[2:3] op_sel_hi:[1,0]
	v_pk_mul_f32 v[154:155], v[78:79], v[154:155]
	v_pk_mul_f32 v[156:157], v[80:81], v[156:157]
	v_pk_mul_f32 v[158:159], v[74:75], v[158:159]
	v_pk_mul_f32 v[160:161], v[76:77], v[160:161]
	v_pk_fma_f32 v[154:155], v[78:79], v[154:155], v[78:79]
	v_pk_fma_f32 v[156:157], v[80:81], v[156:157], v[80:81]
	v_pk_fma_f32 v[158:159], v[74:75], v[158:159], v[74:75]
	v_pk_fma_f32 v[160:161], v[76:77], v[160:161], v[76:77]
	v_pk_mul_f32 v[154:155], v[154:155], s[48:49] op_sel_hi:[1,0]
	v_pk_mul_f32 v[156:157], v[156:157], s[48:49] op_sel_hi:[1,0]
	v_pk_mul_f32 v[158:159], v[158:159], s[48:49] op_sel_hi:[1,0]
	v_pk_mul_f32 v[160:161], v[160:161], s[48:49] op_sel_hi:[1,0]
	v_pk_mul_f32 v[154:155], v[154:155], s[28:29] op_sel_hi:[1,0]
	v_pk_mul_f32 v[156:157], v[156:157], s[28:29] op_sel_hi:[1,0]
	v_pk_mul_f32 v[158:159], v[158:159], s[28:29] op_sel_hi:[1,0]
	v_pk_mul_f32 v[160:161], v[160:161], s[28:29] op_sel_hi:[1,0]
	v_exp_f32_e32 v154, v154
	v_exp_f32_e32 v155, v155
	v_exp_f32_e32 v156, v156
	v_exp_f32_e32 v157, v157
	v_exp_f32_e32 v158, v158
	v_exp_f32_e32 v159, v159
	v_exp_f32_e32 v160, v160
	v_exp_f32_e32 v161, v161
	v_pk_add_f32 v[154:155], v[154:155], s[0:1] op_sel_hi:[1,0]
	v_pk_add_f32 v[156:157], v[156:157], s[0:1] op_sel_hi:[1,0]
	v_pk_add_f32 v[158:159], v[158:159], s[0:1] op_sel_hi:[1,0]
	v_pk_add_f32 v[160:161], v[160:161], s[0:1] op_sel_hi:[1,0]
	v_rcp_f32_e32 v154, v154
	v_rcp_f32_e32 v155, v155
	v_rcp_f32_e32 v156, v156
	v_rcp_f32_e32 v157, v157
	v_rcp_f32_e32 v158, v158
	v_rcp_f32_e32 v159, v159
	v_rcp_f32_e32 v160, v160
	v_rcp_f32_e32 v161, v161
	v_pk_mul_f32 v[78:79], v[78:79], v[154:155]
	v_pk_mul_f32 v[80:81], v[80:81], v[156:157]
	v_pk_mul_f32 v[74:75], v[74:75], v[158:159]
	v_pk_mul_f32 v[76:77], v[76:77], v[160:161]
	v_cvt_pk_bf16_f32 v130, v78, v79
	v_cvt_pk_bf16_f32 v131, v80, v81
	v_cvt_pk_bf16_f32 v132, v74, v75
	v_cvt_pk_bf16_f32 v133, v76, v77
	global_store_dwordx4 v166, v[130:133], s[34:35] nt
	v_pk_mul_f32 v[70:71], v[70:71], v[182:183] op_sel_hi:[1,0]
	v_pk_mul_f32 v[72:73], v[72:73], v[182:183] op_sel_hi:[1,0]
	v_pk_mul_f32 v[66:67], v[66:67], v[182:183] op_sel_hi:[1,0]
	v_pk_mul_f32 v[68:69], v[68:69], v[182:183] op_sel_hi:[1,0]
	v_pk_mul_f32 v[154:155], v[70:71], s[2:3] op_sel_hi:[1,0]
	v_pk_mul_f32 v[156:157], v[72:73], s[2:3] op_sel_hi:[1,0]
	v_pk_mul_f32 v[158:159], v[66:67], s[2:3] op_sel_hi:[1,0]
	v_pk_mul_f32 v[160:161], v[68:69], s[2:3] op_sel_hi:[1,0]
	v_pk_mul_f32 v[154:155], v[70:71], v[154:155]
	v_pk_mul_f32 v[156:157], v[72:73], v[156:157]
	v_pk_mul_f32 v[158:159], v[66:67], v[158:159]
	v_pk_mul_f32 v[160:161], v[68:69], v[160:161]
	v_pk_fma_f32 v[154:155], v[70:71], v[154:155], v[70:71]
	v_pk_fma_f32 v[156:157], v[72:73], v[156:157], v[72:73]
	v_pk_fma_f32 v[158:159], v[66:67], v[158:159], v[66:67]
	v_pk_fma_f32 v[160:161], v[68:69], v[160:161], v[68:69]
	v_pk_mul_f32 v[154:155], v[154:155], s[48:49] op_sel_hi:[1,0]
	v_pk_mul_f32 v[156:157], v[156:157], s[48:49] op_sel_hi:[1,0]
	v_pk_mul_f32 v[158:159], v[158:159], s[48:49] op_sel_hi:[1,0]
	v_pk_mul_f32 v[160:161], v[160:161], s[48:49] op_sel_hi:[1,0]
	v_pk_mul_f32 v[154:155], v[154:155], s[28:29] op_sel_hi:[1,0]
	v_pk_mul_f32 v[156:157], v[156:157], s[28:29] op_sel_hi:[1,0]
	v_pk_mul_f32 v[158:159], v[158:159], s[28:29] op_sel_hi:[1,0]
	v_pk_mul_f32 v[160:161], v[160:161], s[28:29] op_sel_hi:[1,0]
	v_exp_f32_e32 v154, v154
	v_exp_f32_e32 v155, v155
	v_exp_f32_e32 v156, v156
	v_exp_f32_e32 v157, v157
	v_exp_f32_e32 v158, v158
	v_exp_f32_e32 v159, v159
	v_exp_f32_e32 v160, v160
	v_exp_f32_e32 v161, v161
	v_pk_add_f32 v[154:155], v[154:155], s[0:1] op_sel_hi:[1,0]
	v_pk_add_f32 v[156:157], v[156:157], s[0:1] op_sel_hi:[1,0]
	v_pk_add_f32 v[158:159], v[158:159], s[0:1] op_sel_hi:[1,0]
	v_pk_add_f32 v[160:161], v[160:161], s[0:1] op_sel_hi:[1,0]
	v_rcp_f32_e32 v154, v154
	v_rcp_f32_e32 v155, v155
	v_rcp_f32_e32 v156, v156
	v_rcp_f32_e32 v157, v157
	v_rcp_f32_e32 v158, v158
	v_rcp_f32_e32 v159, v159
	v_rcp_f32_e32 v160, v160
	v_rcp_f32_e32 v161, v161
	v_pk_mul_f32 v[70:71], v[70:71], v[154:155]
	v_pk_mul_f32 v[72:73], v[72:73], v[156:157]
	v_pk_mul_f32 v[66:67], v[66:67], v[158:159]
	v_pk_mul_f32 v[68:69], v[68:69], v[160:161]
	v_cvt_pk_bf16_f32 v134, v70, v71
	v_cvt_pk_bf16_f32 v135, v72, v73
	v_cvt_pk_bf16_f32 v136, v66, v67
	v_cvt_pk_bf16_f32 v137, v68, v69
	global_store_dwordx4 v166, v[134:137], s[34:35] offset:256 nt
	v_add_u32_e32 v164, 0x350000, v165
	v_pk_mul_f32 v[62:63], v[62:63], v[184:185] op_sel_hi:[1,0]
	v_pk_mul_f32 v[64:65], v[64:65], v[184:185] op_sel_hi:[1,0]
	v_pk_mul_f32 v[58:59], v[58:59], v[184:185] op_sel_hi:[1,0]
	v_pk_mul_f32 v[60:61], v[60:61], v[184:185] op_sel_hi:[1,0]
	v_pk_mul_f32 v[154:155], v[62:63], s[2:3] op_sel_hi:[1,0]
	v_pk_mul_f32 v[156:157], v[64:65], s[2:3] op_sel_hi:[1,0]
	v_pk_mul_f32 v[158:159], v[58:59], s[2:3] op_sel_hi:[1,0]
	v_pk_mul_f32 v[160:161], v[60:61], s[2:3] op_sel_hi:[1,0]
	v_pk_mul_f32 v[154:155], v[62:63], v[154:155]
	v_pk_mul_f32 v[156:157], v[64:65], v[156:157]
	v_pk_mul_f32 v[158:159], v[58:59], v[158:159]
	v_pk_mul_f32 v[160:161], v[60:61], v[160:161]
	v_pk_fma_f32 v[154:155], v[62:63], v[154:155], v[62:63]
	v_pk_fma_f32 v[156:157], v[64:65], v[156:157], v[64:65]
	v_pk_fma_f32 v[158:159], v[58:59], v[158:159], v[58:59]
	v_pk_fma_f32 v[160:161], v[60:61], v[160:161], v[60:61]
	v_pk_mul_f32 v[154:155], v[154:155], s[48:49] op_sel_hi:[1,0]
	v_pk_mul_f32 v[156:157], v[156:157], s[48:49] op_sel_hi:[1,0]
	v_pk_mul_f32 v[158:159], v[158:159], s[48:49] op_sel_hi:[1,0]
	v_pk_mul_f32 v[160:161], v[160:161], s[48:49] op_sel_hi:[1,0]
	v_pk_mul_f32 v[154:155], v[154:155], s[28:29] op_sel_hi:[1,0]
	v_pk_mul_f32 v[156:157], v[156:157], s[28:29] op_sel_hi:[1,0]
	v_pk_mul_f32 v[158:159], v[158:159], s[28:29] op_sel_hi:[1,0]
	v_pk_mul_f32 v[160:161], v[160:161], s[28:29] op_sel_hi:[1,0]
	v_exp_f32_e32 v154, v154
	v_exp_f32_e32 v155, v155
	v_exp_f32_e32 v156, v156
	v_exp_f32_e32 v157, v157
	v_exp_f32_e32 v158, v158
	v_exp_f32_e32 v159, v159
	v_exp_f32_e32 v160, v160
	v_exp_f32_e32 v161, v161
	v_pk_add_f32 v[154:155], v[154:155], s[0:1] op_sel_hi:[1,0]
	v_pk_add_f32 v[156:157], v[156:157], s[0:1] op_sel_hi:[1,0]
	v_pk_add_f32 v[158:159], v[158:159], s[0:1] op_sel_hi:[1,0]
	v_pk_add_f32 v[160:161], v[160:161], s[0:1] op_sel_hi:[1,0]
	v_rcp_f32_e32 v154, v154
	v_rcp_f32_e32 v155, v155
	v_rcp_f32_e32 v156, v156
	v_rcp_f32_e32 v157, v157
	v_rcp_f32_e32 v158, v158
	v_rcp_f32_e32 v159, v159
	v_rcp_f32_e32 v160, v160
	v_rcp_f32_e32 v161, v161
	v_pk_mul_f32 v[62:63], v[62:63], v[154:155]
	v_pk_mul_f32 v[64:65], v[64:65], v[156:157]
	v_pk_mul_f32 v[58:59], v[58:59], v[158:159]
	v_pk_mul_f32 v[60:61], v[60:61], v[160:161]
	v_cvt_pk_bf16_f32 v130, v62, v63
	v_cvt_pk_bf16_f32 v131, v64, v65
	v_cvt_pk_bf16_f32 v132, v58, v59
	v_cvt_pk_bf16_f32 v133, v60, v61
	global_store_dwordx4 v164, v[130:133], s[34:35] nt
	v_pk_mul_f32 v[54:55], v[54:55], v[184:185] op_sel_hi:[1,0]
	v_pk_mul_f32 v[56:57], v[56:57], v[184:185] op_sel_hi:[1,0]
	v_pk_mul_f32 v[50:51], v[50:51], v[184:185] op_sel_hi:[1,0]
	v_pk_mul_f32 v[52:53], v[52:53], v[184:185] op_sel_hi:[1,0]
	v_pk_mul_f32 v[154:155], v[54:55], s[2:3] op_sel_hi:[1,0]
	v_pk_mul_f32 v[156:157], v[56:57], s[2:3] op_sel_hi:[1,0]
	v_pk_mul_f32 v[158:159], v[50:51], s[2:3] op_sel_hi:[1,0]
	v_pk_mul_f32 v[160:161], v[52:53], s[2:3] op_sel_hi:[1,0]
	v_pk_mul_f32 v[154:155], v[54:55], v[154:155]
	v_pk_mul_f32 v[156:157], v[56:57], v[156:157]
	v_pk_mul_f32 v[158:159], v[50:51], v[158:159]
	v_pk_mul_f32 v[160:161], v[52:53], v[160:161]
	v_pk_fma_f32 v[154:155], v[54:55], v[154:155], v[54:55]
	v_pk_fma_f32 v[156:157], v[56:57], v[156:157], v[56:57]
	v_pk_fma_f32 v[158:159], v[50:51], v[158:159], v[50:51]
	v_pk_fma_f32 v[160:161], v[52:53], v[160:161], v[52:53]
	v_pk_mul_f32 v[154:155], v[154:155], s[48:49] op_sel_hi:[1,0]
	v_pk_mul_f32 v[156:157], v[156:157], s[48:49] op_sel_hi:[1,0]
	v_pk_mul_f32 v[158:159], v[158:159], s[48:49] op_sel_hi:[1,0]
	v_pk_mul_f32 v[160:161], v[160:161], s[48:49] op_sel_hi:[1,0]
	v_pk_mul_f32 v[154:155], v[154:155], s[28:29] op_sel_hi:[1,0]
	v_pk_mul_f32 v[156:157], v[156:157], s[28:29] op_sel_hi:[1,0]
	v_pk_mul_f32 v[158:159], v[158:159], s[28:29] op_sel_hi:[1,0]
	v_pk_mul_f32 v[160:161], v[160:161], s[28:29] op_sel_hi:[1,0]
	v_exp_f32_e32 v154, v154
	v_exp_f32_e32 v155, v155
	v_exp_f32_e32 v156, v156
	v_exp_f32_e32 v157, v157
	v_exp_f32_e32 v158, v158
	v_exp_f32_e32 v159, v159
	v_exp_f32_e32 v160, v160
	v_exp_f32_e32 v161, v161
	v_pk_add_f32 v[154:155], v[154:155], s[0:1] op_sel_hi:[1,0]
	v_pk_add_f32 v[156:157], v[156:157], s[0:1] op_sel_hi:[1,0]
	v_pk_add_f32 v[158:159], v[158:159], s[0:1] op_sel_hi:[1,0]
	v_pk_add_f32 v[160:161], v[160:161], s[0:1] op_sel_hi:[1,0]
	v_rcp_f32_e32 v154, v154
	v_rcp_f32_e32 v155, v155
	v_rcp_f32_e32 v156, v156
	v_rcp_f32_e32 v157, v157
	v_rcp_f32_e32 v158, v158
	v_rcp_f32_e32 v159, v159
	v_rcp_f32_e32 v160, v160
	v_rcp_f32_e32 v161, v161
	v_pk_mul_f32 v[54:55], v[54:55], v[154:155]
	v_pk_mul_f32 v[56:57], v[56:57], v[156:157]
	v_pk_mul_f32 v[50:51], v[50:51], v[158:159]
	v_pk_mul_f32 v[52:53], v[52:53], v[160:161]
	v_cvt_pk_bf16_f32 v134, v54, v55
	v_cvt_pk_bf16_f32 v135, v56, v57
	v_cvt_pk_bf16_f32 v136, v50, v51
	v_cvt_pk_bf16_f32 v137, v52, v53
	global_store_dwordx4 v164, v[134:137], s[34:35] offset:256 nt
	v_add_u32_e32 v166, 0x3ba000, v165
	v_pk_mul_f32 v[46:47], v[46:47], v[186:187] op_sel_hi:[1,0]
	v_pk_mul_f32 v[48:49], v[48:49], v[186:187] op_sel_hi:[1,0]
	v_pk_mul_f32 v[42:43], v[42:43], v[186:187] op_sel_hi:[1,0]
	v_pk_mul_f32 v[44:45], v[44:45], v[186:187] op_sel_hi:[1,0]
	v_pk_mul_f32 v[154:155], v[46:47], s[2:3] op_sel_hi:[1,0]
	v_pk_mul_f32 v[156:157], v[48:49], s[2:3] op_sel_hi:[1,0]
	v_pk_mul_f32 v[158:159], v[42:43], s[2:3] op_sel_hi:[1,0]
	v_pk_mul_f32 v[160:161], v[44:45], s[2:3] op_sel_hi:[1,0]
	v_pk_mul_f32 v[154:155], v[46:47], v[154:155]
	v_pk_mul_f32 v[156:157], v[48:49], v[156:157]
	v_pk_mul_f32 v[158:159], v[42:43], v[158:159]
	v_pk_mul_f32 v[160:161], v[44:45], v[160:161]
	v_pk_fma_f32 v[154:155], v[46:47], v[154:155], v[46:47]
	v_pk_fma_f32 v[156:157], v[48:49], v[156:157], v[48:49]
	v_pk_fma_f32 v[158:159], v[42:43], v[158:159], v[42:43]
	v_pk_fma_f32 v[160:161], v[44:45], v[160:161], v[44:45]
	v_pk_mul_f32 v[154:155], v[154:155], s[48:49] op_sel_hi:[1,0]
	v_pk_mul_f32 v[156:157], v[156:157], s[48:49] op_sel_hi:[1,0]
	v_pk_mul_f32 v[158:159], v[158:159], s[48:49] op_sel_hi:[1,0]
	v_pk_mul_f32 v[160:161], v[160:161], s[48:49] op_sel_hi:[1,0]
	v_pk_mul_f32 v[154:155], v[154:155], s[28:29] op_sel_hi:[1,0]
	v_pk_mul_f32 v[156:157], v[156:157], s[28:29] op_sel_hi:[1,0]
	v_pk_mul_f32 v[158:159], v[158:159], s[28:29] op_sel_hi:[1,0]
	v_pk_mul_f32 v[160:161], v[160:161], s[28:29] op_sel_hi:[1,0]
	v_exp_f32_e32 v154, v154
	v_exp_f32_e32 v155, v155
	v_exp_f32_e32 v156, v156
	v_exp_f32_e32 v157, v157
	v_exp_f32_e32 v158, v158
	v_exp_f32_e32 v159, v159
	v_exp_f32_e32 v160, v160
	v_exp_f32_e32 v161, v161
	v_pk_add_f32 v[154:155], v[154:155], s[0:1] op_sel_hi:[1,0]
	v_pk_add_f32 v[156:157], v[156:157], s[0:1] op_sel_hi:[1,0]
	v_pk_add_f32 v[158:159], v[158:159], s[0:1] op_sel_hi:[1,0]
	v_pk_add_f32 v[160:161], v[160:161], s[0:1] op_sel_hi:[1,0]
	v_rcp_f32_e32 v154, v154
	v_rcp_f32_e32 v155, v155
	v_rcp_f32_e32 v156, v156
	v_rcp_f32_e32 v157, v157
	v_rcp_f32_e32 v158, v158
	v_rcp_f32_e32 v159, v159
	v_rcp_f32_e32 v160, v160
	v_rcp_f32_e32 v161, v161
	v_pk_mul_f32 v[46:47], v[46:47], v[154:155]
	v_pk_mul_f32 v[48:49], v[48:49], v[156:157]
	v_pk_mul_f32 v[42:43], v[42:43], v[158:159]
	v_pk_mul_f32 v[44:45], v[44:45], v[160:161]
	v_cvt_pk_bf16_f32 v130, v46, v47
	v_cvt_pk_bf16_f32 v131, v48, v49
	v_cvt_pk_bf16_f32 v132, v42, v43
	v_cvt_pk_bf16_f32 v133, v44, v45
	global_store_dwordx4 v166, v[130:133], s[34:35] nt
	v_pk_mul_f32 v[38:39], v[38:39], v[186:187] op_sel_hi:[1,0]
	v_pk_mul_f32 v[40:41], v[40:41], v[186:187] op_sel_hi:[1,0]
	v_pk_mul_f32 v[34:35], v[34:35], v[186:187] op_sel_hi:[1,0]
	v_pk_mul_f32 v[36:37], v[36:37], v[186:187] op_sel_hi:[1,0]
	v_pk_mul_f32 v[154:155], v[38:39], s[2:3] op_sel_hi:[1,0]
	v_pk_mul_f32 v[156:157], v[40:41], s[2:3] op_sel_hi:[1,0]
	v_pk_mul_f32 v[158:159], v[34:35], s[2:3] op_sel_hi:[1,0]
	v_pk_mul_f32 v[160:161], v[36:37], s[2:3] op_sel_hi:[1,0]
	v_pk_mul_f32 v[154:155], v[38:39], v[154:155]
	v_pk_mul_f32 v[156:157], v[40:41], v[156:157]
	v_pk_mul_f32 v[158:159], v[34:35], v[158:159]
	v_pk_mul_f32 v[160:161], v[36:37], v[160:161]
	v_pk_fma_f32 v[154:155], v[38:39], v[154:155], v[38:39]
	v_pk_fma_f32 v[156:157], v[40:41], v[156:157], v[40:41]
	v_pk_fma_f32 v[158:159], v[34:35], v[158:159], v[34:35]
	v_pk_fma_f32 v[160:161], v[36:37], v[160:161], v[36:37]
	v_pk_mul_f32 v[154:155], v[154:155], s[48:49] op_sel_hi:[1,0]
	v_pk_mul_f32 v[156:157], v[156:157], s[48:49] op_sel_hi:[1,0]
	v_pk_mul_f32 v[158:159], v[158:159], s[48:49] op_sel_hi:[1,0]
	v_pk_mul_f32 v[160:161], v[160:161], s[48:49] op_sel_hi:[1,0]
	v_pk_mul_f32 v[154:155], v[154:155], s[28:29] op_sel_hi:[1,0]
	v_pk_mul_f32 v[156:157], v[156:157], s[28:29] op_sel_hi:[1,0]
	v_pk_mul_f32 v[158:159], v[158:159], s[28:29] op_sel_hi:[1,0]
	v_pk_mul_f32 v[160:161], v[160:161], s[28:29] op_sel_hi:[1,0]
	v_exp_f32_e32 v154, v154
	v_exp_f32_e32 v155, v155
	v_exp_f32_e32 v156, v156
	v_exp_f32_e32 v157, v157
	v_exp_f32_e32 v158, v158
	v_exp_f32_e32 v159, v159
	v_exp_f32_e32 v160, v160
	v_exp_f32_e32 v161, v161
	v_pk_add_f32 v[154:155], v[154:155], s[0:1] op_sel_hi:[1,0]
	v_pk_add_f32 v[156:157], v[156:157], s[0:1] op_sel_hi:[1,0]
	v_pk_add_f32 v[158:159], v[158:159], s[0:1] op_sel_hi:[1,0]
	v_pk_add_f32 v[160:161], v[160:161], s[0:1] op_sel_hi:[1,0]
	v_rcp_f32_e32 v154, v154
	v_rcp_f32_e32 v155, v155
	v_rcp_f32_e32 v156, v156
	v_rcp_f32_e32 v157, v157
	v_rcp_f32_e32 v158, v158
	v_rcp_f32_e32 v159, v159
	v_rcp_f32_e32 v160, v160
	v_rcp_f32_e32 v161, v161
	v_pk_mul_f32 v[38:39], v[38:39], v[154:155]
	v_pk_mul_f32 v[40:41], v[40:41], v[156:157]
	v_pk_mul_f32 v[34:35], v[34:35], v[158:159]
	v_pk_mul_f32 v[36:37], v[36:37], v[160:161]
	v_cvt_pk_bf16_f32 v134, v38, v39
	v_cvt_pk_bf16_f32 v135, v40, v41
	v_cvt_pk_bf16_f32 v136, v34, v35
	v_cvt_pk_bf16_f32 v137, v36, v37
	global_store_dwordx4 v166, v[134:137], s[34:35] offset:256 nt
	v_add_u32_e32 v164, 0x424000, v165
	v_pk_mul_f32 v[30:31], v[30:31], v[188:189] op_sel_hi:[1,0]
	v_pk_mul_f32 v[32:33], v[32:33], v[188:189] op_sel_hi:[1,0]
	v_pk_mul_f32 v[26:27], v[26:27], v[188:189] op_sel_hi:[1,0]
	v_pk_mul_f32 v[28:29], v[28:29], v[188:189] op_sel_hi:[1,0]
	v_pk_mul_f32 v[154:155], v[30:31], s[2:3] op_sel_hi:[1,0]
	v_pk_mul_f32 v[156:157], v[32:33], s[2:3] op_sel_hi:[1,0]
	v_pk_mul_f32 v[158:159], v[26:27], s[2:3] op_sel_hi:[1,0]
	v_pk_mul_f32 v[160:161], v[28:29], s[2:3] op_sel_hi:[1,0]
	v_pk_mul_f32 v[154:155], v[30:31], v[154:155]
	v_pk_mul_f32 v[156:157], v[32:33], v[156:157]
	v_pk_mul_f32 v[158:159], v[26:27], v[158:159]
	v_pk_mul_f32 v[160:161], v[28:29], v[160:161]
	v_pk_fma_f32 v[154:155], v[30:31], v[154:155], v[30:31]
	v_pk_fma_f32 v[156:157], v[32:33], v[156:157], v[32:33]
	v_pk_fma_f32 v[158:159], v[26:27], v[158:159], v[26:27]
	v_pk_fma_f32 v[160:161], v[28:29], v[160:161], v[28:29]
	v_pk_mul_f32 v[154:155], v[154:155], s[48:49] op_sel_hi:[1,0]
	v_pk_mul_f32 v[156:157], v[156:157], s[48:49] op_sel_hi:[1,0]
	v_pk_mul_f32 v[158:159], v[158:159], s[48:49] op_sel_hi:[1,0]
	v_pk_mul_f32 v[160:161], v[160:161], s[48:49] op_sel_hi:[1,0]
	v_pk_mul_f32 v[154:155], v[154:155], s[28:29] op_sel_hi:[1,0]
	v_pk_mul_f32 v[156:157], v[156:157], s[28:29] op_sel_hi:[1,0]
	v_pk_mul_f32 v[158:159], v[158:159], s[28:29] op_sel_hi:[1,0]
	v_pk_mul_f32 v[160:161], v[160:161], s[28:29] op_sel_hi:[1,0]
	v_exp_f32_e32 v154, v154
	v_exp_f32_e32 v155, v155
	v_exp_f32_e32 v156, v156
	v_exp_f32_e32 v157, v157
	v_exp_f32_e32 v158, v158
	v_exp_f32_e32 v159, v159
	v_exp_f32_e32 v160, v160
	v_exp_f32_e32 v161, v161
	v_pk_add_f32 v[154:155], v[154:155], s[0:1] op_sel_hi:[1,0]
	v_pk_add_f32 v[156:157], v[156:157], s[0:1] op_sel_hi:[1,0]
	v_pk_add_f32 v[158:159], v[158:159], s[0:1] op_sel_hi:[1,0]
	v_pk_add_f32 v[160:161], v[160:161], s[0:1] op_sel_hi:[1,0]
	v_rcp_f32_e32 v154, v154
	v_rcp_f32_e32 v155, v155
	v_rcp_f32_e32 v156, v156
	v_rcp_f32_e32 v157, v157
	v_rcp_f32_e32 v158, v158
	v_rcp_f32_e32 v159, v159
	v_rcp_f32_e32 v160, v160
	v_rcp_f32_e32 v161, v161
	v_pk_mul_f32 v[30:31], v[30:31], v[154:155]
	v_pk_mul_f32 v[32:33], v[32:33], v[156:157]
	v_pk_mul_f32 v[26:27], v[26:27], v[158:159]
	v_pk_mul_f32 v[28:29], v[28:29], v[160:161]
	v_cvt_pk_bf16_f32 v130, v30, v31
	v_cvt_pk_bf16_f32 v131, v32, v33
	v_cvt_pk_bf16_f32 v132, v26, v27
	v_cvt_pk_bf16_f32 v133, v28, v29
	global_store_dwordx4 v164, v[130:133], s[34:35] nt
	v_pk_mul_f32 v[22:23], v[22:23], v[188:189] op_sel_hi:[1,0]
	v_pk_mul_f32 v[24:25], v[24:25], v[188:189] op_sel_hi:[1,0]
	v_pk_mul_f32 v[18:19], v[18:19], v[188:189] op_sel_hi:[1,0]
	v_pk_mul_f32 v[20:21], v[20:21], v[188:189] op_sel_hi:[1,0]
	v_pk_mul_f32 v[154:155], v[22:23], s[2:3] op_sel_hi:[1,0]
	v_pk_mul_f32 v[156:157], v[24:25], s[2:3] op_sel_hi:[1,0]
	v_pk_mul_f32 v[158:159], v[18:19], s[2:3] op_sel_hi:[1,0]
	v_pk_mul_f32 v[160:161], v[20:21], s[2:3] op_sel_hi:[1,0]
	v_pk_mul_f32 v[154:155], v[22:23], v[154:155]
	v_pk_mul_f32 v[156:157], v[24:25], v[156:157]
	v_pk_mul_f32 v[158:159], v[18:19], v[158:159]
	v_pk_mul_f32 v[160:161], v[20:21], v[160:161]
	v_pk_fma_f32 v[154:155], v[22:23], v[154:155], v[22:23]
	v_pk_fma_f32 v[156:157], v[24:25], v[156:157], v[24:25]
	v_pk_fma_f32 v[158:159], v[18:19], v[158:159], v[18:19]
	v_pk_fma_f32 v[160:161], v[20:21], v[160:161], v[20:21]
	v_pk_mul_f32 v[154:155], v[154:155], s[48:49] op_sel_hi:[1,0]
	v_pk_mul_f32 v[156:157], v[156:157], s[48:49] op_sel_hi:[1,0]
	v_pk_mul_f32 v[158:159], v[158:159], s[48:49] op_sel_hi:[1,0]
	v_pk_mul_f32 v[160:161], v[160:161], s[48:49] op_sel_hi:[1,0]
	v_pk_mul_f32 v[154:155], v[154:155], s[28:29] op_sel_hi:[1,0]
	v_pk_mul_f32 v[156:157], v[156:157], s[28:29] op_sel_hi:[1,0]
	v_pk_mul_f32 v[158:159], v[158:159], s[28:29] op_sel_hi:[1,0]
	v_pk_mul_f32 v[160:161], v[160:161], s[28:29] op_sel_hi:[1,0]
	v_exp_f32_e32 v154, v154
	v_exp_f32_e32 v155, v155
	v_exp_f32_e32 v156, v156
	v_exp_f32_e32 v157, v157
	v_exp_f32_e32 v158, v158
	v_exp_f32_e32 v159, v159
	v_exp_f32_e32 v160, v160
	v_exp_f32_e32 v161, v161
	v_pk_add_f32 v[154:155], v[154:155], s[0:1] op_sel_hi:[1,0]
	v_pk_add_f32 v[156:157], v[156:157], s[0:1] op_sel_hi:[1,0]
	v_pk_add_f32 v[158:159], v[158:159], s[0:1] op_sel_hi:[1,0]
	v_pk_add_f32 v[160:161], v[160:161], s[0:1] op_sel_hi:[1,0]
	v_rcp_f32_e32 v154, v154
	v_rcp_f32_e32 v155, v155
	v_rcp_f32_e32 v156, v156
	v_rcp_f32_e32 v157, v157
	v_rcp_f32_e32 v158, v158
	v_rcp_f32_e32 v159, v159
	v_rcp_f32_e32 v160, v160
	v_rcp_f32_e32 v161, v161
	v_pk_mul_f32 v[22:23], v[22:23], v[154:155]
	v_pk_mul_f32 v[24:25], v[24:25], v[156:157]
	v_pk_mul_f32 v[18:19], v[18:19], v[158:159]
	v_pk_mul_f32 v[20:21], v[20:21], v[160:161]
	v_cvt_pk_bf16_f32 v134, v22, v23
	v_cvt_pk_bf16_f32 v135, v24, v25
	v_cvt_pk_bf16_f32 v136, v18, v19
	v_cvt_pk_bf16_f32 v137, v20, v21
	global_store_dwordx4 v164, v[134:137], s[34:35] offset:256 nt
	v_add_u32_e32 v166, 0x48e000, v165
	v_pk_mul_f32 v[14:15], v[14:15], v[190:191] op_sel_hi:[1,0]
	v_pk_mul_f32 v[16:17], v[16:17], v[190:191] op_sel_hi:[1,0]
	v_pk_mul_f32 v[10:11], v[10:11], v[190:191] op_sel_hi:[1,0]
	v_pk_mul_f32 v[12:13], v[12:13], v[190:191] op_sel_hi:[1,0]
	v_pk_mul_f32 v[154:155], v[14:15], s[2:3] op_sel_hi:[1,0]
	v_pk_mul_f32 v[156:157], v[16:17], s[2:3] op_sel_hi:[1,0]
	v_pk_mul_f32 v[158:159], v[10:11], s[2:3] op_sel_hi:[1,0]
	v_pk_mul_f32 v[160:161], v[12:13], s[2:3] op_sel_hi:[1,0]
	v_pk_mul_f32 v[154:155], v[14:15], v[154:155]
	v_pk_mul_f32 v[156:157], v[16:17], v[156:157]
	v_pk_mul_f32 v[158:159], v[10:11], v[158:159]
	v_pk_mul_f32 v[160:161], v[12:13], v[160:161]
	v_pk_fma_f32 v[154:155], v[14:15], v[154:155], v[14:15]
	v_pk_fma_f32 v[156:157], v[16:17], v[156:157], v[16:17]
	v_pk_fma_f32 v[158:159], v[10:11], v[158:159], v[10:11]
	v_pk_fma_f32 v[160:161], v[12:13], v[160:161], v[12:13]
	v_pk_mul_f32 v[154:155], v[154:155], s[48:49] op_sel_hi:[1,0]
	v_pk_mul_f32 v[156:157], v[156:157], s[48:49] op_sel_hi:[1,0]
	v_pk_mul_f32 v[158:159], v[158:159], s[48:49] op_sel_hi:[1,0]
	v_pk_mul_f32 v[160:161], v[160:161], s[48:49] op_sel_hi:[1,0]
	v_pk_mul_f32 v[154:155], v[154:155], s[28:29] op_sel_hi:[1,0]
	v_pk_mul_f32 v[156:157], v[156:157], s[28:29] op_sel_hi:[1,0]
	v_pk_mul_f32 v[158:159], v[158:159], s[28:29] op_sel_hi:[1,0]
	v_pk_mul_f32 v[160:161], v[160:161], s[28:29] op_sel_hi:[1,0]
	v_exp_f32_e32 v154, v154
	v_exp_f32_e32 v155, v155
	v_exp_f32_e32 v156, v156
	v_exp_f32_e32 v157, v157
	v_exp_f32_e32 v158, v158
	v_exp_f32_e32 v159, v159
	v_exp_f32_e32 v160, v160
	v_exp_f32_e32 v161, v161
	v_pk_add_f32 v[154:155], v[154:155], s[0:1] op_sel_hi:[1,0]
	v_pk_add_f32 v[156:157], v[156:157], s[0:1] op_sel_hi:[1,0]
	v_pk_add_f32 v[158:159], v[158:159], s[0:1] op_sel_hi:[1,0]
	v_pk_add_f32 v[160:161], v[160:161], s[0:1] op_sel_hi:[1,0]
	v_rcp_f32_e32 v154, v154
	v_rcp_f32_e32 v155, v155
	v_rcp_f32_e32 v156, v156
	v_rcp_f32_e32 v157, v157
	v_rcp_f32_e32 v158, v158
	v_rcp_f32_e32 v159, v159
	v_rcp_f32_e32 v160, v160
	v_rcp_f32_e32 v161, v161
	v_pk_mul_f32 v[14:15], v[14:15], v[154:155]
	v_pk_mul_f32 v[16:17], v[16:17], v[156:157]
	v_pk_mul_f32 v[10:11], v[10:11], v[158:159]
	v_pk_mul_f32 v[12:13], v[12:13], v[160:161]
	v_cvt_pk_bf16_f32 v130, v14, v15
	v_cvt_pk_bf16_f32 v131, v16, v17
	v_cvt_pk_bf16_f32 v132, v10, v11
	v_cvt_pk_bf16_f32 v133, v12, v13
	global_store_dwordx4 v166, v[130:133], s[34:35] nt
	v_pk_mul_f32 v[6:7], v[6:7], v[190:191] op_sel_hi:[1,0]
	v_pk_mul_f32 v[8:9], v[8:9], v[190:191] op_sel_hi:[1,0]
	v_pk_mul_f32 v[2:3], v[2:3], v[190:191] op_sel_hi:[1,0]
	v_pk_mul_f32 v[4:5], v[4:5], v[190:191] op_sel_hi:[1,0]
	v_pk_mul_f32 v[154:155], v[6:7], s[2:3] op_sel_hi:[1,0]
	v_pk_mul_f32 v[156:157], v[8:9], s[2:3] op_sel_hi:[1,0]
	v_pk_mul_f32 v[158:159], v[2:3], s[2:3] op_sel_hi:[1,0]
	v_pk_mul_f32 v[160:161], v[4:5], s[2:3] op_sel_hi:[1,0]
	v_pk_mul_f32 v[154:155], v[6:7], v[154:155]
	v_pk_mul_f32 v[156:157], v[8:9], v[156:157]
	v_pk_mul_f32 v[158:159], v[2:3], v[158:159]
	v_pk_mul_f32 v[160:161], v[4:5], v[160:161]
	v_pk_fma_f32 v[154:155], v[6:7], v[154:155], v[6:7]
	v_pk_fma_f32 v[156:157], v[8:9], v[156:157], v[8:9]
	v_pk_fma_f32 v[158:159], v[2:3], v[158:159], v[2:3]
	v_pk_fma_f32 v[160:161], v[4:5], v[160:161], v[4:5]
	v_pk_mul_f32 v[154:155], v[154:155], s[48:49] op_sel_hi:[1,0]
	v_pk_mul_f32 v[156:157], v[156:157], s[48:49] op_sel_hi:[1,0]
	v_pk_mul_f32 v[158:159], v[158:159], s[48:49] op_sel_hi:[1,0]
	v_pk_mul_f32 v[160:161], v[160:161], s[48:49] op_sel_hi:[1,0]
	v_pk_mul_f32 v[154:155], v[154:155], s[28:29] op_sel_hi:[1,0]
	v_pk_mul_f32 v[156:157], v[156:157], s[28:29] op_sel_hi:[1,0]
	v_pk_mul_f32 v[158:159], v[158:159], s[28:29] op_sel_hi:[1,0]
	v_pk_mul_f32 v[160:161], v[160:161], s[28:29] op_sel_hi:[1,0]
	v_exp_f32_e32 v154, v154
	v_exp_f32_e32 v155, v155
	v_exp_f32_e32 v156, v156
	v_exp_f32_e32 v157, v157
	v_exp_f32_e32 v158, v158
	v_exp_f32_e32 v159, v159
	v_exp_f32_e32 v160, v160
	v_exp_f32_e32 v161, v161
	v_pk_add_f32 v[154:155], v[154:155], s[0:1] op_sel_hi:[1,0]
	v_pk_add_f32 v[156:157], v[156:157], s[0:1] op_sel_hi:[1,0]
	v_pk_add_f32 v[158:159], v[158:159], s[0:1] op_sel_hi:[1,0]
	v_pk_add_f32 v[160:161], v[160:161], s[0:1] op_sel_hi:[1,0]
	v_rcp_f32_e32 v154, v154
	v_rcp_f32_e32 v155, v155
	v_rcp_f32_e32 v156, v156
	v_rcp_f32_e32 v157, v157
	v_rcp_f32_e32 v158, v158
	v_rcp_f32_e32 v159, v159
	v_rcp_f32_e32 v160, v160
	v_rcp_f32_e32 v161, v161
	v_pk_mul_f32 v[6:7], v[6:7], v[154:155]
	v_pk_mul_f32 v[8:9], v[8:9], v[156:157]
	v_pk_mul_f32 v[2:3], v[2:3], v[158:159]
	v_pk_mul_f32 v[4:5], v[4:5], v[160:161]
	v_cvt_pk_bf16_f32 v134, v6, v7
	v_cvt_pk_bf16_f32 v135, v8, v9
	v_cvt_pk_bf16_f32 v136, v2, v3
	v_cvt_pk_bf16_f32 v137, v4, v5
	global_store_dwordx4 v166, v[134:137], s[34:35] offset:256 nt
	s_branch .Lfe_done
.Lfe_silu:
	v_pk_mul_f32 v[126:127], v[126:127], v[176:177] op_sel_hi:[1,0]
	v_pk_mul_f32 v[128:129], v[128:129], v[176:177] op_sel_hi:[1,0]
	v_pk_mul_f32 v[122:123], v[122:123], v[176:177] op_sel_hi:[1,0]
	v_pk_mul_f32 v[124:125], v[124:125], v[176:177] op_sel_hi:[1,0]
	v_pk_mul_f32 v[154:155], v[126:127], s[28:29] op_sel_hi:[1,0]
	v_pk_mul_f32 v[156:157], v[128:129], s[28:29] op_sel_hi:[1,0]
	v_pk_mul_f32 v[158:159], v[122:123], s[28:29] op_sel_hi:[1,0]
	v_pk_mul_f32 v[160:161], v[124:125], s[28:29] op_sel_hi:[1,0]
	v_exp_f32_e32 v154, v154
	v_exp_f32_e32 v155, v155
	v_exp_f32_e32 v156, v156
	v_exp_f32_e32 v157, v157
	v_exp_f32_e32 v158, v158
	v_exp_f32_e32 v159, v159
	v_exp_f32_e32 v160, v160
	v_exp_f32_e32 v161, v161
	v_pk_add_f32 v[154:155], v[154:155], s[0:1] op_sel_hi:[1,0]
	v_pk_add_f32 v[156:157], v[156:157], s[0:1] op_sel_hi:[1,0]
	v_pk_add_f32 v[158:159], v[158:159], s[0:1] op_sel_hi:[1,0]
	v_pk_add_f32 v[160:161], v[160:161], s[0:1] op_sel_hi:[1,0]
	v_rcp_f32_e32 v154, v154
	v_rcp_f32_e32 v155, v155
	v_rcp_f32_e32 v156, v156
	v_rcp_f32_e32 v157, v157
	v_rcp_f32_e32 v158, v158
	v_rcp_f32_e32 v159, v159
	v_rcp_f32_e32 v160, v160
	v_rcp_f32_e32 v161, v161
	v_pk_mul_f32 v[126:127], v[126:127], v[154:155]
	v_pk_mul_f32 v[128:129], v[128:129], v[156:157]
	v_pk_mul_f32 v[122:123], v[122:123], v[158:159]
	v_pk_mul_f32 v[124:125], v[124:125], v[160:161]
	v_cvt_pk_bf16_f32 v130, v126, v127
	v_cvt_pk_bf16_f32 v131, v128, v129
	v_cvt_pk_bf16_f32 v132, v122, v123
	v_cvt_pk_bf16_f32 v133, v124, v125
	global_store_dwordx4 v165, v[130:133], s[34:35] nt
	v_pk_mul_f32 v[118:119], v[118:119], v[176:177] op_sel_hi:[1,0]
	v_pk_mul_f32 v[120:121], v[120:121], v[176:177] op_sel_hi:[1,0]
	v_pk_mul_f32 v[114:115], v[114:115], v[176:177] op_sel_hi:[1,0]
	v_pk_mul_f32 v[116:117], v[116:117], v[176:177] op_sel_hi:[1,0]
	v_pk_mul_f32 v[154:155], v[118:119], s[28:29] op_sel_hi:[1,0]
	v_pk_mul_f32 v[156:157], v[120:121], s[28:29] op_sel_hi:[1,0]
	v_pk_mul_f32 v[158:159], v[114:115], s[28:29] op_sel_hi:[1,0]
	v_pk_mul_f32 v[160:161], v[116:117], s[28:29] op_sel_hi:[1,0]
	v_exp_f32_e32 v154, v154
	v_exp_f32_e32 v155, v155
	v_exp_f32_e32 v156, v156
	v_exp_f32_e32 v157, v157
	v_exp_f32_e32 v158, v158
	v_exp_f32_e32 v159, v159
	v_exp_f32_e32 v160, v160
	v_exp_f32_e32 v161, v161
	v_pk_add_f32 v[154:155], v[154:155], s[0:1] op_sel_hi:[1,0]
	v_pk_add_f32 v[156:157], v[156:157], s[0:1] op_sel_hi:[1,0]
	v_pk_add_f32 v[158:159], v[158:159], s[0:1] op_sel_hi:[1,0]
	v_pk_add_f32 v[160:161], v[160:161], s[0:1] op_sel_hi:[1,0]
	v_rcp_f32_e32 v154, v154
	v_rcp_f32_e32 v155, v155
	v_rcp_f32_e32 v156, v156
	v_rcp_f32_e32 v157, v157
	v_rcp_f32_e32 v158, v158
	v_rcp_f32_e32 v159, v159
	v_rcp_f32_e32 v160, v160
	v_rcp_f32_e32 v161, v161
	v_pk_mul_f32 v[118:119], v[118:119], v[154:155]
	v_pk_mul_f32 v[120:121], v[120:121], v[156:157]
	v_pk_mul_f32 v[114:115], v[114:115], v[158:159]
	v_pk_mul_f32 v[116:117], v[116:117], v[160:161]
	v_cvt_pk_bf16_f32 v134, v118, v119
	v_cvt_pk_bf16_f32 v135, v120, v121
	v_cvt_pk_bf16_f32 v136, v114, v115
	v_cvt_pk_bf16_f32 v137, v116, v117
	global_store_dwordx4 v165, v[134:137], s[34:35] offset:256 nt
	v_add_u32_e32 v166, 0x6a000, v165
	v_pk_mul_f32 v[110:111], v[110:111], v[178:179] op_sel_hi:[1,0]
	v_pk_mul_f32 v[112:113], v[112:113], v[178:179] op_sel_hi:[1,0]
	v_pk_mul_f32 v[106:107], v[106:107], v[178:179] op_sel_hi:[1,0]
	v_pk_mul_f32 v[108:109], v[108:109], v[178:179] op_sel_hi:[1,0]
	v_pk_mul_f32 v[154:155], v[110:111], s[28:29] op_sel_hi:[1,0]
	v_pk_mul_f32 v[156:157], v[112:113], s[28:29] op_sel_hi:[1,0]
	v_pk_mul_f32 v[158:159], v[106:107], s[28:29] op_sel_hi:[1,0]
	v_pk_mul_f32 v[160:161], v[108:109], s[28:29] op_sel_hi:[1,0]
	v_exp_f32_e32 v154, v154
	v_exp_f32_e32 v155, v155
	v_exp_f32_e32 v156, v156
	v_exp_f32_e32 v157, v157
	v_exp_f32_e32 v158, v158
	v_exp_f32_e32 v159, v159
	v_exp_f32_e32 v160, v160
	v_exp_f32_e32 v161, v161
	v_pk_add_f32 v[154:155], v[154:155], s[0:1] op_sel_hi:[1,0]
	v_pk_add_f32 v[156:157], v[156:157], s[0:1] op_sel_hi:[1,0]
	v_pk_add_f32 v[158:159], v[158:159], s[0:1] op_sel_hi:[1,0]
	v_pk_add_f32 v[160:161], v[160:161], s[0:1] op_sel_hi:[1,0]
	v_rcp_f32_e32 v154, v154
	v_rcp_f32_e32 v155, v155
	v_rcp_f32_e32 v156, v156
	v_rcp_f32_e32 v157, v157
	v_rcp_f32_e32 v158, v158
	v_rcp_f32_e32 v159, v159
	v_rcp_f32_e32 v160, v160
	v_rcp_f32_e32 v161, v161
	v_pk_mul_f32 v[110:111], v[110:111], v[154:155]
	v_pk_mul_f32 v[112:113], v[112:113], v[156:157]
	v_pk_mul_f32 v[106:107], v[106:107], v[158:159]
	v_pk_mul_f32 v[108:109], v[108:109], v[160:161]
	v_cvt_pk_bf16_f32 v130, v110, v111
	v_cvt_pk_bf16_f32 v131, v112, v113
	v_cvt_pk_bf16_f32 v132, v106, v107
	v_cvt_pk_bf16_f32 v133, v108, v109
	global_store_dwordx4 v166, v[130:133], s[34:35] nt
	v_pk_mul_f32 v[102:103], v[102:103], v[178:179] op_sel_hi:[1,0]
	v_pk_mul_f32 v[104:105], v[104:105], v[178:179] op_sel_hi:[1,0]
	v_pk_mul_f32 v[98:99], v[98:99], v[178:179] op_sel_hi:[1,0]
	v_pk_mul_f32 v[100:101], v[100:101], v[178:179] op_sel_hi:[1,0]
	v_pk_mul_f32 v[154:155], v[102:103], s[28:29] op_sel_hi:[1,0]
	v_pk_mul_f32 v[156:157], v[104:105], s[28:29] op_sel_hi:[1,0]
	v_pk_mul_f32 v[158:159], v[98:99], s[28:29] op_sel_hi:[1,0]
	v_pk_mul_f32 v[160:161], v[100:101], s[28:29] op_sel_hi:[1,0]
	v_exp_f32_e32 v154, v154
	v_exp_f32_e32 v155, v155
	v_exp_f32_e32 v156, v156
	v_exp_f32_e32 v157, v157
	v_exp_f32_e32 v158, v158
	v_exp_f32_e32 v159, v159
	v_exp_f32_e32 v160, v160
	v_exp_f32_e32 v161, v161
	v_pk_add_f32 v[154:155], v[154:155], s[0:1] op_sel_hi:[1,0]
	v_pk_add_f32 v[156:157], v[156:157], s[0:1] op_sel_hi:[1,0]
	v_pk_add_f32 v[158:159], v[158:159], s[0:1] op_sel_hi:[1,0]
	v_pk_add_f32 v[160:161], v[160:161], s[0:1] op_sel_hi:[1,0]
	v_rcp_f32_e32 v154, v154
	v_rcp_f32_e32 v155, v155
	v_rcp_f32_e32 v156, v156
	v_rcp_f32_e32 v157, v157
	v_rcp_f32_e32 v158, v158
	v_rcp_f32_e32 v159, v159
	v_rcp_f32_e32 v160, v160
	v_rcp_f32_e32 v161, v161
	v_pk_mul_f32 v[102:103], v[102:103], v[154:155]
	v_pk_mul_f32 v[104:105], v[104:105], v[156:157]
	v_pk_mul_f32 v[98:99], v[98:99], v[158:159]
	v_pk_mul_f32 v[100:101], v[100:101], v[160:161]
	v_cvt_pk_bf16_f32 v134, v102, v103
	v_cvt_pk_bf16_f32 v135, v104, v105
	v_cvt_pk_bf16_f32 v136, v98, v99
	v_cvt_pk_bf16_f32 v137, v100, v101
	global_store_dwordx4 v166, v[134:137], s[34:35] offset:256 nt
	v_add_u32_e32 v164, 0xd4000, v165
	v_pk_mul_f32 v[94:95], v[94:95], v[180:181] op_sel_hi:[1,0]
	v_pk_mul_f32 v[96:97], v[96:97], v[180:181] op_sel_hi:[1,0]
	v_pk_mul_f32 v[90:91], v[90:91], v[180:181] op_sel_hi:[1,0]
	v_pk_mul_f32 v[92:93], v[92:93], v[180:181] op_sel_hi:[1,0]
	v_pk_mul_f32 v[154:155], v[94:95], s[28:29] op_sel_hi:[1,0]
	v_pk_mul_f32 v[156:157], v[96:97], s[28:29] op_sel_hi:[1,0]
	v_pk_mul_f32 v[158:159], v[90:91], s[28:29] op_sel_hi:[1,0]
	v_pk_mul_f32 v[160:161], v[92:93], s[28:29] op_sel_hi:[1,0]
	v_exp_f32_e32 v154, v154
	v_exp_f32_e32 v155, v155
	v_exp_f32_e32 v156, v156
	v_exp_f32_e32 v157, v157
	v_exp_f32_e32 v158, v158
	v_exp_f32_e32 v159, v159
	v_exp_f32_e32 v160, v160
	v_exp_f32_e32 v161, v161
	v_pk_add_f32 v[154:155], v[154:155], s[0:1] op_sel_hi:[1,0]
	v_pk_add_f32 v[156:157], v[156:157], s[0:1] op_sel_hi:[1,0]
	v_pk_add_f32 v[158:159], v[158:159], s[0:1] op_sel_hi:[1,0]
	v_pk_add_f32 v[160:161], v[160:161], s[0:1] op_sel_hi:[1,0]
	v_rcp_f32_e32 v154, v154
	v_rcp_f32_e32 v155, v155
	v_rcp_f32_e32 v156, v156
	v_rcp_f32_e32 v157, v157
	v_rcp_f32_e32 v158, v158
	v_rcp_f32_e32 v159, v159
	v_rcp_f32_e32 v160, v160
	v_rcp_f32_e32 v161, v161
	v_pk_mul_f32 v[94:95], v[94:95], v[154:155]
	v_pk_mul_f32 v[96:97], v[96:97], v[156:157]
	v_pk_mul_f32 v[90:91], v[90:91], v[158:159]
	v_pk_mul_f32 v[92:93], v[92:93], v[160:161]
	v_cvt_pk_bf16_f32 v130, v94, v95
	v_cvt_pk_bf16_f32 v131, v96, v97
	v_cvt_pk_bf16_f32 v132, v90, v91
	v_cvt_pk_bf16_f32 v133, v92, v93
	global_store_dwordx4 v164, v[130:133], s[34:35] nt
	v_pk_mul_f32 v[86:87], v[86:87], v[180:181] op_sel_hi:[1,0]
	v_pk_mul_f32 v[88:89], v[88:89], v[180:181] op_sel_hi:[1,0]
	v_pk_mul_f32 v[82:83], v[82:83], v[180:181] op_sel_hi:[1,0]
	v_pk_mul_f32 v[84:85], v[84:85], v[180:181] op_sel_hi:[1,0]
	v_pk_mul_f32 v[154:155], v[86:87], s[28:29] op_sel_hi:[1,0]
	v_pk_mul_f32 v[156:157], v[88:89], s[28:29] op_sel_hi:[1,0]
	v_pk_mul_f32 v[158:159], v[82:83], s[28:29] op_sel_hi:[1,0]
	v_pk_mul_f32 v[160:161], v[84:85], s[28:29] op_sel_hi:[1,0]
	v_exp_f32_e32 v154, v154
	v_exp_f32_e32 v155, v155
	v_exp_f32_e32 v156, v156
	v_exp_f32_e32 v157, v157
	v_exp_f32_e32 v158, v158
	v_exp_f32_e32 v159, v159
	v_exp_f32_e32 v160, v160
	v_exp_f32_e32 v161, v161
	v_pk_add_f32 v[154:155], v[154:155], s[0:1] op_sel_hi:[1,0]
	v_pk_add_f32 v[156:157], v[156:157], s[0:1] op_sel_hi:[1,0]
	v_pk_add_f32 v[158:159], v[158:159], s[0:1] op_sel_hi:[1,0]
	v_pk_add_f32 v[160:161], v[160:161], s[0:1] op_sel_hi:[1,0]
	v_rcp_f32_e32 v154, v154
	v_rcp_f32_e32 v155, v155
	v_rcp_f32_e32 v156, v156
	v_rcp_f32_e32 v157, v157
	v_rcp_f32_e32 v158, v158
	v_rcp_f32_e32 v159, v159
	v_rcp_f32_e32 v160, v160
	v_rcp_f32_e32 v161, v161
	v_pk_mul_f32 v[86:87], v[86:87], v[154:155]
	v_pk_mul_f32 v[88:89], v[88:89], v[156:157]
	v_pk_mul_f32 v[82:83], v[82:83], v[158:159]
	v_pk_mul_f32 v[84:85], v[84:85], v[160:161]
	v_cvt_pk_bf16_f32 v134, v86, v87
	v_cvt_pk_bf16_f32 v135, v88, v89
	v_cvt_pk_bf16_f32 v136, v82, v83
	v_cvt_pk_bf16_f32 v137, v84, v85
	global_store_dwordx4 v164, v[134:137], s[34:35] offset:256 nt
	v_add_u32_e32 v166, 0x13e000, v165
	v_pk_mul_f32 v[78:79], v[78:79], v[182:183] op_sel_hi:[1,0]
	v_pk_mul_f32 v[80:81], v[80:81], v[182:183] op_sel_hi:[1,0]
	v_pk_mul_f32 v[74:75], v[74:75], v[182:183] op_sel_hi:[1,0]
	v_pk_mul_f32 v[76:77], v[76:77], v[182:183] op_sel_hi:[1,0]
	v_pk_mul_f32 v[154:155], v[78:79], s[28:29] op_sel_hi:[1,0]
	v_pk_mul_f32 v[156:157], v[80:81], s[28:29] op_sel_hi:[1,0]
	v_pk_mul_f32 v[158:159], v[74:75], s[28:29] op_sel_hi:[1,0]
	v_pk_mul_f32 v[160:161], v[76:77], s[28:29] op_sel_hi:[1,0]
	v_exp_f32_e32 v154, v154
	v_exp_f32_e32 v155, v155
	v_exp_f32_e32 v156, v156
	v_exp_f32_e32 v157, v157
	v_exp_f32_e32 v158, v158
	v_exp_f32_e32 v159, v159
	v_exp_f32_e32 v160, v160
	v_exp_f32_e32 v161, v161
	v_pk_add_f32 v[154:155], v[154:155], s[0:1] op_sel_hi:[1,0]
	v_pk_add_f32 v[156:157], v[156:157], s[0:1] op_sel_hi:[1,0]
	v_pk_add_f32 v[158:159], v[158:159], s[0:1] op_sel_hi:[1,0]
	v_pk_add_f32 v[160:161], v[160:161], s[0:1] op_sel_hi:[1,0]
	v_rcp_f32_e32 v154, v154
	v_rcp_f32_e32 v155, v155
	v_rcp_f32_e32 v156, v156
	v_rcp_f32_e32 v157, v157
	v_rcp_f32_e32 v158, v158
	v_rcp_f32_e32 v159, v159
	v_rcp_f32_e32 v160, v160
	v_rcp_f32_e32 v161, v161
	v_pk_mul_f32 v[78:79], v[78:79], v[154:155]
	v_pk_mul_f32 v[80:81], v[80:81], v[156:157]
	v_pk_mul_f32 v[74:75], v[74:75], v[158:159]
	v_pk_mul_f32 v[76:77], v[76:77], v[160:161]
	v_cvt_pk_bf16_f32 v130, v78, v79
	v_cvt_pk_bf16_f32 v131, v80, v81
	v_cvt_pk_bf16_f32 v132, v74, v75
	v_cvt_pk_bf16_f32 v133, v76, v77
	global_store_dwordx4 v166, v[130:133], s[34:35] nt
	v_pk_mul_f32 v[70:71], v[70:71], v[182:183] op_sel_hi:[1,0]
	v_pk_mul_f32 v[72:73], v[72:73], v[182:183] op_sel_hi:[1,0]
	v_pk_mul_f32 v[66:67], v[66:67], v[182:183] op_sel_hi:[1,0]
	v_pk_mul_f32 v[68:69], v[68:69], v[182:183] op_sel_hi:[1,0]
	v_pk_mul_f32 v[154:155], v[70:71], s[28:29] op_sel_hi:[1,0]
	v_pk_mul_f32 v[156:157], v[72:73], s[28:29] op_sel_hi:[1,0]
	v_pk_mul_f32 v[158:159], v[66:67], s[28:29] op_sel_hi:[1,0]
	v_pk_mul_f32 v[160:161], v[68:69], s[28:29] op_sel_hi:[1,0]
	v_exp_f32_e32 v154, v154
	v_exp_f32_e32 v155, v155
	v_exp_f32_e32 v156, v156
	v_exp_f32_e32 v157, v157
	v_exp_f32_e32 v158, v158
	v_exp_f32_e32 v159, v159
	v_exp_f32_e32 v160, v160
	v_exp_f32_e32 v161, v161
	v_pk_add_f32 v[154:155], v[154:155], s[0:1] op_sel_hi:[1,0]
	v_pk_add_f32 v[156:157], v[156:157], s[0:1] op_sel_hi:[1,0]
	v_pk_add_f32 v[158:159], v[158:159], s[0:1] op_sel_hi:[1,0]
	v_pk_add_f32 v[160:161], v[160:161], s[0:1] op_sel_hi:[1,0]
	v_rcp_f32_e32 v154, v154
	v_rcp_f32_e32 v155, v155
	v_rcp_f32_e32 v156, v156
	v_rcp_f32_e32 v157, v157
	v_rcp_f32_e32 v158, v158
	v_rcp_f32_e32 v159, v159
	v_rcp_f32_e32 v160, v160
	v_rcp_f32_e32 v161, v161
	v_pk_mul_f32 v[70:71], v[70:71], v[154:155]
	v_pk_mul_f32 v[72:73], v[72:73], v[156:157]
	v_pk_mul_f32 v[66:67], v[66:67], v[158:159]
	v_pk_mul_f32 v[68:69], v[68:69], v[160:161]
	v_cvt_pk_bf16_f32 v134, v70, v71
	v_cvt_pk_bf16_f32 v135, v72, v73
	v_cvt_pk_bf16_f32 v136, v66, v67
	v_cvt_pk_bf16_f32 v137, v68, v69
	global_store_dwordx4 v166, v[134:137], s[34:35] offset:256 nt
	v_add_u32_e32 v164, 0x350000, v165
	v_pk_mul_f32 v[62:63], v[62:63], v[184:185] op_sel_hi:[1,0]
	v_pk_mul_f32 v[64:65], v[64:65], v[184:185] op_sel_hi:[1,0]
	v_pk_mul_f32 v[58:59], v[58:59], v[184:185] op_sel_hi:[1,0]
	v_pk_mul_f32 v[60:61], v[60:61], v[184:185] op_sel_hi:[1,0]
	v_pk_mul_f32 v[154:155], v[62:63], s[28:29] op_sel_hi:[1,0]
	v_pk_mul_f32 v[156:157], v[64:65], s[28:29] op_sel_hi:[1,0]
	v_pk_mul_f32 v[158:159], v[58:59], s[28:29] op_sel_hi:[1,0]
	v_pk_mul_f32 v[160:161], v[60:61], s[28:29] op_sel_hi:[1,0]
	v_exp_f32_e32 v154, v154
	v_exp_f32_e32 v155, v155
	v_exp_f32_e32 v156, v156
	v_exp_f32_e32 v157, v157
	v_exp_f32_e32 v158, v158
	v_exp_f32_e32 v159, v159
	v_exp_f32_e32 v160, v160
	v_exp_f32_e32 v161, v161
	v_pk_add_f32 v[154:155], v[154:155], s[0:1] op_sel_hi:[1,0]
	v_pk_add_f32 v[156:157], v[156:157], s[0:1] op_sel_hi:[1,0]
	v_pk_add_f32 v[158:159], v[158:159], s[0:1] op_sel_hi:[1,0]
	v_pk_add_f32 v[160:161], v[160:161], s[0:1] op_sel_hi:[1,0]
	v_rcp_f32_e32 v154, v154
	v_rcp_f32_e32 v155, v155
	v_rcp_f32_e32 v156, v156
	v_rcp_f32_e32 v157, v157
	v_rcp_f32_e32 v158, v158
	v_rcp_f32_e32 v159, v159
	v_rcp_f32_e32 v160, v160
	v_rcp_f32_e32 v161, v161
	v_pk_mul_f32 v[62:63], v[62:63], v[154:155]
	v_pk_mul_f32 v[64:65], v[64:65], v[156:157]
	v_pk_mul_f32 v[58:59], v[58:59], v[158:159]
	v_pk_mul_f32 v[60:61], v[60:61], v[160:161]
	v_cvt_pk_bf16_f32 v130, v62, v63
	v_cvt_pk_bf16_f32 v131, v64, v65
	v_cvt_pk_bf16_f32 v132, v58, v59
	v_cvt_pk_bf16_f32 v133, v60, v61
	global_store_dwordx4 v164, v[130:133], s[34:35] nt
	v_pk_mul_f32 v[54:55], v[54:55], v[184:185] op_sel_hi:[1,0]
	v_pk_mul_f32 v[56:57], v[56:57], v[184:185] op_sel_hi:[1,0]
	v_pk_mul_f32 v[50:51], v[50:51], v[184:185] op_sel_hi:[1,0]
	v_pk_mul_f32 v[52:53], v[52:53], v[184:185] op_sel_hi:[1,0]
	v_pk_mul_f32 v[154:155], v[54:55], s[28:29] op_sel_hi:[1,0]
	v_pk_mul_f32 v[156:157], v[56:57], s[28:29] op_sel_hi:[1,0]
	v_pk_mul_f32 v[158:159], v[50:51], s[28:29] op_sel_hi:[1,0]
	v_pk_mul_f32 v[160:161], v[52:53], s[28:29] op_sel_hi:[1,0]
	v_exp_f32_e32 v154, v154
	v_exp_f32_e32 v155, v155
	v_exp_f32_e32 v156, v156
	v_exp_f32_e32 v157, v157
	v_exp_f32_e32 v158, v158
	v_exp_f32_e32 v159, v159
	v_exp_f32_e32 v160, v160
	v_exp_f32_e32 v161, v161
	v_pk_add_f32 v[154:155], v[154:155], s[0:1] op_sel_hi:[1,0]
	v_pk_add_f32 v[156:157], v[156:157], s[0:1] op_sel_hi:[1,0]
	v_pk_add_f32 v[158:159], v[158:159], s[0:1] op_sel_hi:[1,0]
	v_pk_add_f32 v[160:161], v[160:161], s[0:1] op_sel_hi:[1,0]
	v_rcp_f32_e32 v154, v154
	v_rcp_f32_e32 v155, v155
	v_rcp_f32_e32 v156, v156
	v_rcp_f32_e32 v157, v157
	v_rcp_f32_e32 v158, v158
	v_rcp_f32_e32 v159, v159
	v_rcp_f32_e32 v160, v160
	v_rcp_f32_e32 v161, v161
	v_pk_mul_f32 v[54:55], v[54:55], v[154:155]
	v_pk_mul_f32 v[56:57], v[56:57], v[156:157]
	v_pk_mul_f32 v[50:51], v[50:51], v[158:159]
	v_pk_mul_f32 v[52:53], v[52:53], v[160:161]
	v_cvt_pk_bf16_f32 v134, v54, v55
	v_cvt_pk_bf16_f32 v135, v56, v57
	v_cvt_pk_bf16_f32 v136, v50, v51
	v_cvt_pk_bf16_f32 v137, v52, v53
	global_store_dwordx4 v164, v[134:137], s[34:35] offset:256 nt
	v_add_u32_e32 v166, 0x3ba000, v165
	v_pk_mul_f32 v[46:47], v[46:47], v[186:187] op_sel_hi:[1,0]
	v_pk_mul_f32 v[48:49], v[48:49], v[186:187] op_sel_hi:[1,0]
	v_pk_mul_f32 v[42:43], v[42:43], v[186:187] op_sel_hi:[1,0]
	v_pk_mul_f32 v[44:45], v[44:45], v[186:187] op_sel_hi:[1,0]
	v_pk_mul_f32 v[154:155], v[46:47], s[28:29] op_sel_hi:[1,0]
	v_pk_mul_f32 v[156:157], v[48:49], s[28:29] op_sel_hi:[1,0]
	v_pk_mul_f32 v[158:159], v[42:43], s[28:29] op_sel_hi:[1,0]
	v_pk_mul_f32 v[160:161], v[44:45], s[28:29] op_sel_hi:[1,0]
	v_exp_f32_e32 v154, v154
	v_exp_f32_e32 v155, v155
	v_exp_f32_e32 v156, v156
	v_exp_f32_e32 v157, v157
	v_exp_f32_e32 v158, v158
	v_exp_f32_e32 v159, v159
	v_exp_f32_e32 v160, v160
	v_exp_f32_e32 v161, v161
	v_pk_add_f32 v[154:155], v[154:155], s[0:1] op_sel_hi:[1,0]
	v_pk_add_f32 v[156:157], v[156:157], s[0:1] op_sel_hi:[1,0]
	v_pk_add_f32 v[158:159], v[158:159], s[0:1] op_sel_hi:[1,0]
	v_pk_add_f32 v[160:161], v[160:161], s[0:1] op_sel_hi:[1,0]
	v_rcp_f32_e32 v154, v154
	v_rcp_f32_e32 v155, v155
	v_rcp_f32_e32 v156, v156
	v_rcp_f32_e32 v157, v157
	v_rcp_f32_e32 v158, v158
	v_rcp_f32_e32 v159, v159
	v_rcp_f32_e32 v160, v160
	v_rcp_f32_e32 v161, v161
	v_pk_mul_f32 v[46:47], v[46:47], v[154:155]
	v_pk_mul_f32 v[48:49], v[48:49], v[156:157]
	v_pk_mul_f32 v[42:43], v[42:43], v[158:159]
	v_pk_mul_f32 v[44:45], v[44:45], v[160:161]
	v_cvt_pk_bf16_f32 v130, v46, v47
	v_cvt_pk_bf16_f32 v131, v48, v49
	v_cvt_pk_bf16_f32 v132, v42, v43
	v_cvt_pk_bf16_f32 v133, v44, v45
	global_store_dwordx4 v166, v[130:133], s[34:35] nt
	v_pk_mul_f32 v[38:39], v[38:39], v[186:187] op_sel_hi:[1,0]
	v_pk_mul_f32 v[40:41], v[40:41], v[186:187] op_sel_hi:[1,0]
	v_pk_mul_f32 v[34:35], v[34:35], v[186:187] op_sel_hi:[1,0]
	v_pk_mul_f32 v[36:37], v[36:37], v[186:187] op_sel_hi:[1,0]
	v_pk_mul_f32 v[154:155], v[38:39], s[28:29] op_sel_hi:[1,0]
	v_pk_mul_f32 v[156:157], v[40:41], s[28:29] op_sel_hi:[1,0]
	v_pk_mul_f32 v[158:159], v[34:35], s[28:29] op_sel_hi:[1,0]
	v_pk_mul_f32 v[160:161], v[36:37], s[28:29] op_sel_hi:[1,0]
	v_exp_f32_e32 v154, v154
	v_exp_f32_e32 v155, v155
	v_exp_f32_e32 v156, v156
	v_exp_f32_e32 v157, v157
	v_exp_f32_e32 v158, v158
	v_exp_f32_e32 v159, v159
	v_exp_f32_e32 v160, v160
	v_exp_f32_e32 v161, v161
	v_pk_add_f32 v[154:155], v[154:155], s[0:1] op_sel_hi:[1,0]
	v_pk_add_f32 v[156:157], v[156:157], s[0:1] op_sel_hi:[1,0]
	v_pk_add_f32 v[158:159], v[158:159], s[0:1] op_sel_hi:[1,0]
	v_pk_add_f32 v[160:161], v[160:161], s[0:1] op_sel_hi:[1,0]
	v_rcp_f32_e32 v154, v154
	v_rcp_f32_e32 v155, v155
	v_rcp_f32_e32 v156, v156
	v_rcp_f32_e32 v157, v157
	v_rcp_f32_e32 v158, v158
	v_rcp_f32_e32 v159, v159
	v_rcp_f32_e32 v160, v160
	v_rcp_f32_e32 v161, v161
	v_pk_mul_f32 v[38:39], v[38:39], v[154:155]
	v_pk_mul_f32 v[40:41], v[40:41], v[156:157]
	v_pk_mul_f32 v[34:35], v[34:35], v[158:159]
	v_pk_mul_f32 v[36:37], v[36:37], v[160:161]
	v_cvt_pk_bf16_f32 v134, v38, v39
	v_cvt_pk_bf16_f32 v135, v40, v41
	v_cvt_pk_bf16_f32 v136, v34, v35
	v_cvt_pk_bf16_f32 v137, v36, v37
	global_store_dwordx4 v166, v[134:137], s[34:35] offset:256 nt
	v_add_u32_e32 v164, 0x424000, v165
	v_pk_mul_f32 v[30:31], v[30:31], v[188:189] op_sel_hi:[1,0]
	v_pk_mul_f32 v[32:33], v[32:33], v[188:189] op_sel_hi:[1,0]
	v_pk_mul_f32 v[26:27], v[26:27], v[188:189] op_sel_hi:[1,0]
	v_pk_mul_f32 v[28:29], v[28:29], v[188:189] op_sel_hi:[1,0]
	v_pk_mul_f32 v[154:155], v[30:31], s[28:29] op_sel_hi:[1,0]
	v_pk_mul_f32 v[156:157], v[32:33], s[28:29] op_sel_hi:[1,0]
	v_pk_mul_f32 v[158:159], v[26:27], s[28:29] op_sel_hi:[1,0]
	v_pk_mul_f32 v[160:161], v[28:29], s[28:29] op_sel_hi:[1,0]
	v_exp_f32_e32 v154, v154
	v_exp_f32_e32 v155, v155
	v_exp_f32_e32 v156, v156
	v_exp_f32_e32 v157, v157
	v_exp_f32_e32 v158, v158
	v_exp_f32_e32 v159, v159
	v_exp_f32_e32 v160, v160
	v_exp_f32_e32 v161, v161
	v_pk_add_f32 v[154:155], v[154:155], s[0:1] op_sel_hi:[1,0]
	v_pk_add_f32 v[156:157], v[156:157], s[0:1] op_sel_hi:[1,0]
	v_pk_add_f32 v[158:159], v[158:159], s[0:1] op_sel_hi:[1,0]
	v_pk_add_f32 v[160:161], v[160:161], s[0:1] op_sel_hi:[1,0]
	v_rcp_f32_e32 v154, v154
	v_rcp_f32_e32 v155, v155
	v_rcp_f32_e32 v156, v156
	v_rcp_f32_e32 v157, v157
	v_rcp_f32_e32 v158, v158
	v_rcp_f32_e32 v159, v159
	v_rcp_f32_e32 v160, v160
	v_rcp_f32_e32 v161, v161
	v_pk_mul_f32 v[30:31], v[30:31], v[154:155]
	v_pk_mul_f32 v[32:33], v[32:33], v[156:157]
	v_pk_mul_f32 v[26:27], v[26:27], v[158:159]
	v_pk_mul_f32 v[28:29], v[28:29], v[160:161]
	v_cvt_pk_bf16_f32 v130, v30, v31
	v_cvt_pk_bf16_f32 v131, v32, v33
	v_cvt_pk_bf16_f32 v132, v26, v27
	v_cvt_pk_bf16_f32 v133, v28, v29
	global_store_dwordx4 v164, v[130:133], s[34:35] nt
	v_pk_mul_f32 v[22:23], v[22:23], v[188:189] op_sel_hi:[1,0]
	v_pk_mul_f32 v[24:25], v[24:25], v[188:189] op_sel_hi:[1,0]
	v_pk_mul_f32 v[18:19], v[18:19], v[188:189] op_sel_hi:[1,0]
	v_pk_mul_f32 v[20:21], v[20:21], v[188:189] op_sel_hi:[1,0]
	v_pk_mul_f32 v[154:155], v[22:23], s[28:29] op_sel_hi:[1,0]
	v_pk_mul_f32 v[156:157], v[24:25], s[28:29] op_sel_hi:[1,0]
	v_pk_mul_f32 v[158:159], v[18:19], s[28:29] op_sel_hi:[1,0]
	v_pk_mul_f32 v[160:161], v[20:21], s[28:29] op_sel_hi:[1,0]
	v_exp_f32_e32 v154, v154
	v_exp_f32_e32 v155, v155
	v_exp_f32_e32 v156, v156
	v_exp_f32_e32 v157, v157
	v_exp_f32_e32 v158, v158
	v_exp_f32_e32 v159, v159
	v_exp_f32_e32 v160, v160
	v_exp_f32_e32 v161, v161
	v_pk_add_f32 v[154:155], v[154:155], s[0:1] op_sel_hi:[1,0]
	v_pk_add_f32 v[156:157], v[156:157], s[0:1] op_sel_hi:[1,0]
	v_pk_add_f32 v[158:159], v[158:159], s[0:1] op_sel_hi:[1,0]
	v_pk_add_f32 v[160:161], v[160:161], s[0:1] op_sel_hi:[1,0]
	v_rcp_f32_e32 v154, v154
	v_rcp_f32_e32 v155, v155
	v_rcp_f32_e32 v156, v156
	v_rcp_f32_e32 v157, v157
	v_rcp_f32_e32 v158, v158
	v_rcp_f32_e32 v159, v159
	v_rcp_f32_e32 v160, v160
	v_rcp_f32_e32 v161, v161
	v_pk_mul_f32 v[22:23], v[22:23], v[154:155]
	v_pk_mul_f32 v[24:25], v[24:25], v[156:157]
	v_pk_mul_f32 v[18:19], v[18:19], v[158:159]
	v_pk_mul_f32 v[20:21], v[20:21], v[160:161]
	v_cvt_pk_bf16_f32 v134, v22, v23
	v_cvt_pk_bf16_f32 v135, v24, v25
	v_cvt_pk_bf16_f32 v136, v18, v19
	v_cvt_pk_bf16_f32 v137, v20, v21
	global_store_dwordx4 v164, v[134:137], s[34:35] offset:256 nt
	v_add_u32_e32 v166, 0x48e000, v165
	v_pk_mul_f32 v[14:15], v[14:15], v[190:191] op_sel_hi:[1,0]
	v_pk_mul_f32 v[16:17], v[16:17], v[190:191] op_sel_hi:[1,0]
	v_pk_mul_f32 v[10:11], v[10:11], v[190:191] op_sel_hi:[1,0]
	v_pk_mul_f32 v[12:13], v[12:13], v[190:191] op_sel_hi:[1,0]
	v_pk_mul_f32 v[154:155], v[14:15], s[28:29] op_sel_hi:[1,0]
	v_pk_mul_f32 v[156:157], v[16:17], s[28:29] op_sel_hi:[1,0]
	v_pk_mul_f32 v[158:159], v[10:11], s[28:29] op_sel_hi:[1,0]
	v_pk_mul_f32 v[160:161], v[12:13], s[28:29] op_sel_hi:[1,0]
	v_exp_f32_e32 v154, v154
	v_exp_f32_e32 v155, v155
	v_exp_f32_e32 v156, v156
	v_exp_f32_e32 v157, v157
	v_exp_f32_e32 v158, v158
	v_exp_f32_e32 v159, v159
	v_exp_f32_e32 v160, v160
	v_exp_f32_e32 v161, v161
	v_pk_add_f32 v[154:155], v[154:155], s[0:1] op_sel_hi:[1,0]
	v_pk_add_f32 v[156:157], v[156:157], s[0:1] op_sel_hi:[1,0]
	v_pk_add_f32 v[158:159], v[158:159], s[0:1] op_sel_hi:[1,0]
	v_pk_add_f32 v[160:161], v[160:161], s[0:1] op_sel_hi:[1,0]
	v_rcp_f32_e32 v154, v154
	v_rcp_f32_e32 v155, v155
	v_rcp_f32_e32 v156, v156
	v_rcp_f32_e32 v157, v157
	v_rcp_f32_e32 v158, v158
	v_rcp_f32_e32 v159, v159
	v_rcp_f32_e32 v160, v160
	v_rcp_f32_e32 v161, v161
	v_pk_mul_f32 v[14:15], v[14:15], v[154:155]
	v_pk_mul_f32 v[16:17], v[16:17], v[156:157]
	v_pk_mul_f32 v[10:11], v[10:11], v[158:159]
	v_pk_mul_f32 v[12:13], v[12:13], v[160:161]
	v_cvt_pk_bf16_f32 v130, v14, v15
	v_cvt_pk_bf16_f32 v131, v16, v17
	v_cvt_pk_bf16_f32 v132, v10, v11
	v_cvt_pk_bf16_f32 v133, v12, v13
	global_store_dwordx4 v166, v[130:133], s[34:35] nt
	v_pk_mul_f32 v[6:7], v[6:7], v[190:191] op_sel_hi:[1,0]
	v_pk_mul_f32 v[8:9], v[8:9], v[190:191] op_sel_hi:[1,0]
	v_pk_mul_f32 v[2:3], v[2:3], v[190:191] op_sel_hi:[1,0]
	v_pk_mul_f32 v[4:5], v[4:5], v[190:191] op_sel_hi:[1,0]
	v_pk_mul_f32 v[154:155], v[6:7], s[28:29] op_sel_hi:[1,0]
	v_pk_mul_f32 v[156:157], v[8:9], s[28:29] op_sel_hi:[1,0]
	v_pk_mul_f32 v[158:159], v[2:3], s[28:29] op_sel_hi:[1,0]
	v_pk_mul_f32 v[160:161], v[4:5], s[28:29] op_sel_hi:[1,0]
	v_exp_f32_e32 v154, v154
	v_exp_f32_e32 v155, v155
	v_exp_f32_e32 v156, v156
	v_exp_f32_e32 v157, v157
	v_exp_f32_e32 v158, v158
	v_exp_f32_e32 v159, v159
	v_exp_f32_e32 v160, v160
	v_exp_f32_e32 v161, v161
	v_pk_add_f32 v[154:155], v[154:155], s[0:1] op_sel_hi:[1,0]
	v_pk_add_f32 v[156:157], v[156:157], s[0:1] op_sel_hi:[1,0]
	v_pk_add_f32 v[158:159], v[158:159], s[0:1] op_sel_hi:[1,0]
	v_pk_add_f32 v[160:161], v[160:161], s[0:1] op_sel_hi:[1,0]
	v_rcp_f32_e32 v154, v154
	v_rcp_f32_e32 v155, v155
	v_rcp_f32_e32 v156, v156
	v_rcp_f32_e32 v157, v157
	v_rcp_f32_e32 v158, v158
	v_rcp_f32_e32 v159, v159
	v_rcp_f32_e32 v160, v160
	v_rcp_f32_e32 v161, v161
	v_pk_mul_f32 v[6:7], v[6:7], v[154:155]
	v_pk_mul_f32 v[8:9], v[8:9], v[156:157]
	v_pk_mul_f32 v[2:3], v[2:3], v[158:159]
	v_pk_mul_f32 v[4:5], v[4:5], v[160:161]
	v_cvt_pk_bf16_f32 v134, v6, v7
	v_cvt_pk_bf16_f32 v135, v8, v9
	v_cvt_pk_bf16_f32 v136, v2, v3
	v_cvt_pk_bf16_f32 v137, v4, v5
	global_store_dwordx4 v166, v[134:137], s[34:35] offset:256 nt
	s_branch .Lfe_done
.Lfe_sig:
	v_pk_mul_f32 v[126:127], v[126:127], v[176:177] op_sel_hi:[1,0]
	v_pk_mul_f32 v[128:129], v[128:129], v[176:177] op_sel_hi:[1,0]
	v_pk_mul_f32 v[122:123], v[122:123], v[176:177] op_sel_hi:[1,0]
	v_pk_mul_f32 v[124:125], v[124:125], v[176:177] op_sel_hi:[1,0]
	v_pk_mul_f32 v[126:127], v[126:127], s[28:29] op_sel_hi:[1,0]
	v_pk_mul_f32 v[128:129], v[128:129], s[28:29] op_sel_hi:[1,0]
	v_pk_mul_f32 v[122:123], v[122:123], s[28:29] op_sel_hi:[1,0]
	v_pk_mul_f32 v[124:125], v[124:125], s[28:29] op_sel_hi:[1,0]
	v_exp_f32_e32 v126, v126
	v_exp_f32_e32 v127, v127
	v_exp_f32_e32 v128, v128
	v_exp_f32_e32 v129, v129
	v_exp_f32_e32 v122, v122
	v_exp_f32_e32 v123, v123
	v_exp_f32_e32 v124, v124
	v_exp_f32_e32 v125, v125
	v_pk_add_f32 v[126:127], v[126:127], s[0:1] op_sel_hi:[1,0]
	v_pk_add_f32 v[128:129], v[128:129], s[0:1] op_sel_hi:[1,0]
	v_pk_add_f32 v[122:123], v[122:123], s[0:1] op_sel_hi:[1,0]
	v_pk_add_f32 v[124:125], v[124:125], s[0:1] op_sel_hi:[1,0]
	v_rcp_f32_e32 v126, v126
	v_rcp_f32_e32 v127, v127
	v_rcp_f32_e32 v128, v128
	v_rcp_f32_e32 v129, v129
	v_rcp_f32_e32 v122, v122
	v_rcp_f32_e32 v123, v123
	v_rcp_f32_e32 v124, v124
	v_rcp_f32_e32 v125, v125
	v_cvt_pk_bf16_f32 v130, v126, v127
	v_cvt_pk_bf16_f32 v131, v128, v129
	v_cvt_pk_bf16_f32 v132, v122, v123
	v_cvt_pk_bf16_f32 v133, v124, v125
	global_store_dwordx4 v165, v[130:133], s[34:35] nt
	v_pk_mul_f32 v[118:119], v[118:119], v[176:177] op_sel_hi:[1,0]
	v_pk_mul_f32 v[120:121], v[120:121], v[176:177] op_sel_hi:[1,0]
	v_pk_mul_f32 v[114:115], v[114:115], v[176:177] op_sel_hi:[1,0]
	v_pk_mul_f32 v[116:117], v[116:117], v[176:177] op_sel_hi:[1,0]
	v_pk_mul_f32 v[118:119], v[118:119], s[28:29] op_sel_hi:[1,0]
	v_pk_mul_f32 v[120:121], v[120:121], s[28:29] op_sel_hi:[1,0]
	v_pk_mul_f32 v[114:115], v[114:115], s[28:29] op_sel_hi:[1,0]
	v_pk_mul_f32 v[116:117], v[116:117], s[28:29] op_sel_hi:[1,0]
	v_exp_f32_e32 v118, v118
	v_exp_f32_e32 v119, v119
	v_exp_f32_e32 v120, v120
	v_exp_f32_e32 v121, v121
	v_exp_f32_e32 v114, v114
	v_exp_f32_e32 v115, v115
	v_exp_f32_e32 v116, v116
	v_exp_f32_e32 v117, v117
	v_pk_add_f32 v[118:119], v[118:119], s[0:1] op_sel_hi:[1,0]
	v_pk_add_f32 v[120:121], v[120:121], s[0:1] op_sel_hi:[1,0]
	v_pk_add_f32 v[114:115], v[114:115], s[0:1] op_sel_hi:[1,0]
	v_pk_add_f32 v[116:117], v[116:117], s[0:1] op_sel_hi:[1,0]
	v_rcp_f32_e32 v118, v118
	v_rcp_f32_e32 v119, v119
	v_rcp_f32_e32 v120, v120
	v_rcp_f32_e32 v121, v121
	v_rcp_f32_e32 v114, v114
	v_rcp_f32_e32 v115, v115
	v_rcp_f32_e32 v116, v116
	v_rcp_f32_e32 v117, v117
	v_cvt_pk_bf16_f32 v134, v118, v119
	v_cvt_pk_bf16_f32 v135, v120, v121
	v_cvt_pk_bf16_f32 v136, v114, v115
	v_cvt_pk_bf16_f32 v137, v116, v117
	global_store_dwordx4 v165, v[134:137], s[34:35] offset:256 nt
	v_add_u32_e32 v166, 0x6a000, v165
	v_pk_mul_f32 v[110:111], v[110:111], v[178:179] op_sel_hi:[1,0]
	v_pk_mul_f32 v[112:113], v[112:113], v[178:179] op_sel_hi:[1,0]
	v_pk_mul_f32 v[106:107], v[106:107], v[178:179] op_sel_hi:[1,0]
	v_pk_mul_f32 v[108:109], v[108:109], v[178:179] op_sel_hi:[1,0]
	v_pk_mul_f32 v[110:111], v[110:111], s[28:29] op_sel_hi:[1,0]
	v_pk_mul_f32 v[112:113], v[112:113], s[28:29] op_sel_hi:[1,0]
	v_pk_mul_f32 v[106:107], v[106:107], s[28:29] op_sel_hi:[1,0]
	v_pk_mul_f32 v[108:109], v[108:109], s[28:29] op_sel_hi:[1,0]
	v_exp_f32_e32 v110, v110
	v_exp_f32_e32 v111, v111
	v_exp_f32_e32 v112, v112
	v_exp_f32_e32 v113, v113
	v_exp_f32_e32 v106, v106
	v_exp_f32_e32 v107, v107
	v_exp_f32_e32 v108, v108
	v_exp_f32_e32 v109, v109
	v_pk_add_f32 v[110:111], v[110:111], s[0:1] op_sel_hi:[1,0]
	v_pk_add_f32 v[112:113], v[112:113], s[0:1] op_sel_hi:[1,0]
	v_pk_add_f32 v[106:107], v[106:107], s[0:1] op_sel_hi:[1,0]
	v_pk_add_f32 v[108:109], v[108:109], s[0:1] op_sel_hi:[1,0]
	v_rcp_f32_e32 v110, v110
	v_rcp_f32_e32 v111, v111
	v_rcp_f32_e32 v112, v112
	v_rcp_f32_e32 v113, v113
	v_rcp_f32_e32 v106, v106
	v_rcp_f32_e32 v107, v107
	v_rcp_f32_e32 v108, v108
	v_rcp_f32_e32 v109, v109
	v_cvt_pk_bf16_f32 v130, v110, v111
	v_cvt_pk_bf16_f32 v131, v112, v113
	v_cvt_pk_bf16_f32 v132, v106, v107
	v_cvt_pk_bf16_f32 v133, v108, v109
	global_store_dwordx4 v166, v[130:133], s[34:35] nt
	v_pk_mul_f32 v[102:103], v[102:103], v[178:179] op_sel_hi:[1,0]
	v_pk_mul_f32 v[104:105], v[104:105], v[178:179] op_sel_hi:[1,0]
	v_pk_mul_f32 v[98:99], v[98:99], v[178:179] op_sel_hi:[1,0]
	v_pk_mul_f32 v[100:101], v[100:101], v[178:179] op_sel_hi:[1,0]
	v_pk_mul_f32 v[102:103], v[102:103], s[28:29] op_sel_hi:[1,0]
	v_pk_mul_f32 v[104:105], v[104:105], s[28:29] op_sel_hi:[1,0]
	v_pk_mul_f32 v[98:99], v[98:99], s[28:29] op_sel_hi:[1,0]
	v_pk_mul_f32 v[100:101], v[100:101], s[28:29] op_sel_hi:[1,0]
	v_exp_f32_e32 v102, v102
	v_exp_f32_e32 v103, v103
	v_exp_f32_e32 v104, v104
	v_exp_f32_e32 v105, v105
	v_exp_f32_e32 v98, v98
	v_exp_f32_e32 v99, v99
	v_exp_f32_e32 v100, v100
	v_exp_f32_e32 v101, v101
	v_pk_add_f32 v[102:103], v[102:103], s[0:1] op_sel_hi:[1,0]
	v_pk_add_f32 v[104:105], v[104:105], s[0:1] op_sel_hi:[1,0]
	v_pk_add_f32 v[98:99], v[98:99], s[0:1] op_sel_hi:[1,0]
	v_pk_add_f32 v[100:101], v[100:101], s[0:1] op_sel_hi:[1,0]
	v_rcp_f32_e32 v102, v102
	v_rcp_f32_e32 v103, v103
	v_rcp_f32_e32 v104, v104
	v_rcp_f32_e32 v105, v105
	v_rcp_f32_e32 v98, v98
	v_rcp_f32_e32 v99, v99
	v_rcp_f32_e32 v100, v100
	v_rcp_f32_e32 v101, v101
	v_cvt_pk_bf16_f32 v134, v102, v103
	v_cvt_pk_bf16_f32 v135, v104, v105
	v_cvt_pk_bf16_f32 v136, v98, v99
	v_cvt_pk_bf16_f32 v137, v100, v101
	global_store_dwordx4 v166, v[134:137], s[34:35] offset:256 nt
	v_add_u32_e32 v164, 0xd4000, v165
	v_pk_mul_f32 v[94:95], v[94:95], v[180:181] op_sel_hi:[1,0]
	v_pk_mul_f32 v[96:97], v[96:97], v[180:181] op_sel_hi:[1,0]
	v_pk_mul_f32 v[90:91], v[90:91], v[180:181] op_sel_hi:[1,0]
	v_pk_mul_f32 v[92:93], v[92:93], v[180:181] op_sel_hi:[1,0]
	v_pk_mul_f32 v[94:95], v[94:95], s[28:29] op_sel_hi:[1,0]
	v_pk_mul_f32 v[96:97], v[96:97], s[28:29] op_sel_hi:[1,0]
	v_pk_mul_f32 v[90:91], v[90:91], s[28:29] op_sel_hi:[1,0]
	v_pk_mul_f32 v[92:93], v[92:93], s[28:29] op_sel_hi:[1,0]
	v_exp_f32_e32 v94, v94
	v_exp_f32_e32 v95, v95
	v_exp_f32_e32 v96, v96
	v_exp_f32_e32 v97, v97
	v_exp_f32_e32 v90, v90
	v_exp_f32_e32 v91, v91
	v_exp_f32_e32 v92, v92
	v_exp_f32_e32 v93, v93
	v_pk_add_f32 v[94:95], v[94:95], s[0:1] op_sel_hi:[1,0]
	v_pk_add_f32 v[96:97], v[96:97], s[0:1] op_sel_hi:[1,0]
	v_pk_add_f32 v[90:91], v[90:91], s[0:1] op_sel_hi:[1,0]
	v_pk_add_f32 v[92:93], v[92:93], s[0:1] op_sel_hi:[1,0]
	v_rcp_f32_e32 v94, v94
	v_rcp_f32_e32 v95, v95
	v_rcp_f32_e32 v96, v96
	v_rcp_f32_e32 v97, v97
	v_rcp_f32_e32 v90, v90
	v_rcp_f32_e32 v91, v91
	v_rcp_f32_e32 v92, v92
	v_rcp_f32_e32 v93, v93
	v_cvt_pk_bf16_f32 v130, v94, v95
	v_cvt_pk_bf16_f32 v131, v96, v97
	v_cvt_pk_bf16_f32 v132, v90, v91
	v_cvt_pk_bf16_f32 v133, v92, v93
	global_store_dwordx4 v164, v[130:133], s[34:35] nt
	v_pk_mul_f32 v[86:87], v[86:87], v[180:181] op_sel_hi:[1,0]
	v_pk_mul_f32 v[88:89], v[88:89], v[180:181] op_sel_hi:[1,0]
	v_pk_mul_f32 v[82:83], v[82:83], v[180:181] op_sel_hi:[1,0]
	v_pk_mul_f32 v[84:85], v[84:85], v[180:181] op_sel_hi:[1,0]
	v_pk_mul_f32 v[86:87], v[86:87], s[28:29] op_sel_hi:[1,0]
	v_pk_mul_f32 v[88:89], v[88:89], s[28:29] op_sel_hi:[1,0]
	v_pk_mul_f32 v[82:83], v[82:83], s[28:29] op_sel_hi:[1,0]
	v_pk_mul_f32 v[84:85], v[84:85], s[28:29] op_sel_hi:[1,0]
	v_exp_f32_e32 v86, v86
	v_exp_f32_e32 v87, v87
	v_exp_f32_e32 v88, v88
	v_exp_f32_e32 v89, v89
	v_exp_f32_e32 v82, v82
	v_exp_f32_e32 v83, v83
	v_exp_f32_e32 v84, v84
	v_exp_f32_e32 v85, v85
	v_pk_add_f32 v[86:87], v[86:87], s[0:1] op_sel_hi:[1,0]
	v_pk_add_f32 v[88:89], v[88:89], s[0:1] op_sel_hi:[1,0]
	v_pk_add_f32 v[82:83], v[82:83], s[0:1] op_sel_hi:[1,0]
	v_pk_add_f32 v[84:85], v[84:85], s[0:1] op_sel_hi:[1,0]
	v_rcp_f32_e32 v86, v86
	v_rcp_f32_e32 v87, v87
	v_rcp_f32_e32 v88, v88
	v_rcp_f32_e32 v89, v89
	v_rcp_f32_e32 v82, v82
	v_rcp_f32_e32 v83, v83
	v_rcp_f32_e32 v84, v84
	v_rcp_f32_e32 v85, v85
	v_cvt_pk_bf16_f32 v134, v86, v87
	v_cvt_pk_bf16_f32 v135, v88, v89
	v_cvt_pk_bf16_f32 v136, v82, v83
	v_cvt_pk_bf16_f32 v137, v84, v85
	global_store_dwordx4 v164, v[134:137], s[34:35] offset:256 nt
	v_add_u32_e32 v166, 0x13e000, v165
	v_pk_mul_f32 v[78:79], v[78:79], v[182:183] op_sel_hi:[1,0]
	v_pk_mul_f32 v[80:81], v[80:81], v[182:183] op_sel_hi:[1,0]
	v_pk_mul_f32 v[74:75], v[74:75], v[182:183] op_sel_hi:[1,0]
	v_pk_mul_f32 v[76:77], v[76:77], v[182:183] op_sel_hi:[1,0]
	v_pk_mul_f32 v[78:79], v[78:79], s[28:29] op_sel_hi:[1,0]
	v_pk_mul_f32 v[80:81], v[80:81], s[28:29] op_sel_hi:[1,0]
	v_pk_mul_f32 v[74:75], v[74:75], s[28:29] op_sel_hi:[1,0]
	v_pk_mul_f32 v[76:77], v[76:77], s[28:29] op_sel_hi:[1,0]
	v_exp_f32_e32 v78, v78
	v_exp_f32_e32 v79, v79
	v_exp_f32_e32 v80, v80
	v_exp_f32_e32 v81, v81
	v_exp_f32_e32 v74, v74
	v_exp_f32_e32 v75, v75
	v_exp_f32_e32 v76, v76
	v_exp_f32_e32 v77, v77
	v_pk_add_f32 v[78:79], v[78:79], s[0:1] op_sel_hi:[1,0]
	v_pk_add_f32 v[80:81], v[80:81], s[0:1] op_sel_hi:[1,0]
	v_pk_add_f32 v[74:75], v[74:75], s[0:1] op_sel_hi:[1,0]
	v_pk_add_f32 v[76:77], v[76:77], s[0:1] op_sel_hi:[1,0]
	v_rcp_f32_e32 v78, v78
	v_rcp_f32_e32 v79, v79
	v_rcp_f32_e32 v80, v80
	v_rcp_f32_e32 v81, v81
	v_rcp_f32_e32 v74, v74
	v_rcp_f32_e32 v75, v75
	v_rcp_f32_e32 v76, v76
	v_rcp_f32_e32 v77, v77
	v_cvt_pk_bf16_f32 v130, v78, v79
	v_cvt_pk_bf16_f32 v131, v80, v81
	v_cvt_pk_bf16_f32 v132, v74, v75
	v_cvt_pk_bf16_f32 v133, v76, v77
	global_store_dwordx4 v166, v[130:133], s[34:35] nt
	v_pk_mul_f32 v[70:71], v[70:71], v[182:183] op_sel_hi:[1,0]
	v_pk_mul_f32 v[72:73], v[72:73], v[182:183] op_sel_hi:[1,0]
	v_pk_mul_f32 v[66:67], v[66:67], v[182:183] op_sel_hi:[1,0]
	v_pk_mul_f32 v[68:69], v[68:69], v[182:183] op_sel_hi:[1,0]
	v_pk_mul_f32 v[70:71], v[70:71], s[28:29] op_sel_hi:[1,0]
	v_pk_mul_f32 v[72:73], v[72:73], s[28:29] op_sel_hi:[1,0]
	v_pk_mul_f32 v[66:67], v[66:67], s[28:29] op_sel_hi:[1,0]
	v_pk_mul_f32 v[68:69], v[68:69], s[28:29] op_sel_hi:[1,0]
	v_exp_f32_e32 v70, v70
	v_exp_f32_e32 v71, v71
	v_exp_f32_e32 v72, v72
	v_exp_f32_e32 v73, v73
	v_exp_f32_e32 v66, v66
	v_exp_f32_e32 v67, v67
	v_exp_f32_e32 v68, v68
	v_exp_f32_e32 v69, v69
	v_pk_add_f32 v[70:71], v[70:71], s[0:1] op_sel_hi:[1,0]
	v_pk_add_f32 v[72:73], v[72:73], s[0:1] op_sel_hi:[1,0]
	v_pk_add_f32 v[66:67], v[66:67], s[0:1] op_sel_hi:[1,0]
	v_pk_add_f32 v[68:69], v[68:69], s[0:1] op_sel_hi:[1,0]
	v_rcp_f32_e32 v70, v70
	v_rcp_f32_e32 v71, v71
	v_rcp_f32_e32 v72, v72
	v_rcp_f32_e32 v73, v73
	v_rcp_f32_e32 v66, v66
	v_rcp_f32_e32 v67, v67
	v_rcp_f32_e32 v68, v68
	v_rcp_f32_e32 v69, v69
	v_cvt_pk_bf16_f32 v134, v70, v71
	v_cvt_pk_bf16_f32 v135, v72, v73
	v_cvt_pk_bf16_f32 v136, v66, v67
	v_cvt_pk_bf16_f32 v137, v68, v69
	global_store_dwordx4 v166, v[134:137], s[34:35] offset:256 nt
	v_add_u32_e32 v164, 0x350000, v165
	v_pk_mul_f32 v[62:63], v[62:63], v[184:185] op_sel_hi:[1,0]
	v_pk_mul_f32 v[64:65], v[64:65], v[184:185] op_sel_hi:[1,0]
	v_pk_mul_f32 v[58:59], v[58:59], v[184:185] op_sel_hi:[1,0]
	v_pk_mul_f32 v[60:61], v[60:61], v[184:185] op_sel_hi:[1,0]
	v_pk_mul_f32 v[62:63], v[62:63], s[28:29] op_sel_hi:[1,0]
	v_pk_mul_f32 v[64:65], v[64:65], s[28:29] op_sel_hi:[1,0]
	v_pk_mul_f32 v[58:59], v[58:59], s[28:29] op_sel_hi:[1,0]
	v_pk_mul_f32 v[60:61], v[60:61], s[28:29] op_sel_hi:[1,0]
	v_exp_f32_e32 v62, v62
	v_exp_f32_e32 v63, v63
	v_exp_f32_e32 v64, v64
	v_exp_f32_e32 v65, v65
	v_exp_f32_e32 v58, v58
	v_exp_f32_e32 v59, v59
	v_exp_f32_e32 v60, v60
	v_exp_f32_e32 v61, v61
	v_pk_add_f32 v[62:63], v[62:63], s[0:1] op_sel_hi:[1,0]
	v_pk_add_f32 v[64:65], v[64:65], s[0:1] op_sel_hi:[1,0]
	v_pk_add_f32 v[58:59], v[58:59], s[0:1] op_sel_hi:[1,0]
	v_pk_add_f32 v[60:61], v[60:61], s[0:1] op_sel_hi:[1,0]
	v_rcp_f32_e32 v62, v62
	v_rcp_f32_e32 v63, v63
	v_rcp_f32_e32 v64, v64
	v_rcp_f32_e32 v65, v65
	v_rcp_f32_e32 v58, v58
	v_rcp_f32_e32 v59, v59
	v_rcp_f32_e32 v60, v60
	v_rcp_f32_e32 v61, v61
	v_cvt_pk_bf16_f32 v130, v62, v63
	v_cvt_pk_bf16_f32 v131, v64, v65
	v_cvt_pk_bf16_f32 v132, v58, v59
	v_cvt_pk_bf16_f32 v133, v60, v61
	global_store_dwordx4 v164, v[130:133], s[34:35] nt
	v_pk_mul_f32 v[54:55], v[54:55], v[184:185] op_sel_hi:[1,0]
	v_pk_mul_f32 v[56:57], v[56:57], v[184:185] op_sel_hi:[1,0]
	v_pk_mul_f32 v[50:51], v[50:51], v[184:185] op_sel_hi:[1,0]
	v_pk_mul_f32 v[52:53], v[52:53], v[184:185] op_sel_hi:[1,0]
	v_pk_mul_f32 v[54:55], v[54:55], s[28:29] op_sel_hi:[1,0]
	v_pk_mul_f32 v[56:57], v[56:57], s[28:29] op_sel_hi:[1,0]
	v_pk_mul_f32 v[50:51], v[50:51], s[28:29] op_sel_hi:[1,0]
	v_pk_mul_f32 v[52:53], v[52:53], s[28:29] op_sel_hi:[1,0]
	v_exp_f32_e32 v54, v54
	v_exp_f32_e32 v55, v55
	v_exp_f32_e32 v56, v56
	v_exp_f32_e32 v57, v57
	v_exp_f32_e32 v50, v50
	v_exp_f32_e32 v51, v51
	v_exp_f32_e32 v52, v52
	v_exp_f32_e32 v53, v53
	v_pk_add_f32 v[54:55], v[54:55], s[0:1] op_sel_hi:[1,0]
	v_pk_add_f32 v[56:57], v[56:57], s[0:1] op_sel_hi:[1,0]
	v_pk_add_f32 v[50:51], v[50:51], s[0:1] op_sel_hi:[1,0]
	v_pk_add_f32 v[52:53], v[52:53], s[0:1] op_sel_hi:[1,0]
	v_rcp_f32_e32 v54, v54
	v_rcp_f32_e32 v55, v55
	v_rcp_f32_e32 v56, v56
	v_rcp_f32_e32 v57, v57
	v_rcp_f32_e32 v50, v50
	v_rcp_f32_e32 v51, v51
	v_rcp_f32_e32 v52, v52
	v_rcp_f32_e32 v53, v53
	v_cvt_pk_bf16_f32 v134, v54, v55
	v_cvt_pk_bf16_f32 v135, v56, v57
	v_cvt_pk_bf16_f32 v136, v50, v51
	v_cvt_pk_bf16_f32 v137, v52, v53
	global_store_dwordx4 v164, v[134:137], s[34:35] offset:256 nt
	v_add_u32_e32 v166, 0x3ba000, v165
	v_pk_mul_f32 v[46:47], v[46:47], v[186:187] op_sel_hi:[1,0]
	v_pk_mul_f32 v[48:49], v[48:49], v[186:187] op_sel_hi:[1,0]
	v_pk_mul_f32 v[42:43], v[42:43], v[186:187] op_sel_hi:[1,0]
	v_pk_mul_f32 v[44:45], v[44:45], v[186:187] op_sel_hi:[1,0]
	v_pk_mul_f32 v[46:47], v[46:47], s[28:29] op_sel_hi:[1,0]
	v_pk_mul_f32 v[48:49], v[48:49], s[28:29] op_sel_hi:[1,0]
	v_pk_mul_f32 v[42:43], v[42:43], s[28:29] op_sel_hi:[1,0]
	v_pk_mul_f32 v[44:45], v[44:45], s[28:29] op_sel_hi:[1,0]
	v_exp_f32_e32 v46, v46
	v_exp_f32_e32 v47, v47
	v_exp_f32_e32 v48, v48
	v_exp_f32_e32 v49, v49
	v_exp_f32_e32 v42, v42
	v_exp_f32_e32 v43, v43
	v_exp_f32_e32 v44, v44
	v_exp_f32_e32 v45, v45
	v_pk_add_f32 v[46:47], v[46:47], s[0:1] op_sel_hi:[1,0]
	v_pk_add_f32 v[48:49], v[48:49], s[0:1] op_sel_hi:[1,0]
	v_pk_add_f32 v[42:43], v[42:43], s[0:1] op_sel_hi:[1,0]
	v_pk_add_f32 v[44:45], v[44:45], s[0:1] op_sel_hi:[1,0]
	v_rcp_f32_e32 v46, v46
	v_rcp_f32_e32 v47, v47
	v_rcp_f32_e32 v48, v48
	v_rcp_f32_e32 v49, v49
	v_rcp_f32_e32 v42, v42
	v_rcp_f32_e32 v43, v43
	v_rcp_f32_e32 v44, v44
	v_rcp_f32_e32 v45, v45
	v_cvt_pk_bf16_f32 v130, v46, v47
	v_cvt_pk_bf16_f32 v131, v48, v49
	v_cvt_pk_bf16_f32 v132, v42, v43
	v_cvt_pk_bf16_f32 v133, v44, v45
	global_store_dwordx4 v166, v[130:133], s[34:35] nt
	v_pk_mul_f32 v[38:39], v[38:39], v[186:187] op_sel_hi:[1,0]
	v_pk_mul_f32 v[40:41], v[40:41], v[186:187] op_sel_hi:[1,0]
	v_pk_mul_f32 v[34:35], v[34:35], v[186:187] op_sel_hi:[1,0]
	v_pk_mul_f32 v[36:37], v[36:37], v[186:187] op_sel_hi:[1,0]
	v_pk_mul_f32 v[38:39], v[38:39], s[28:29] op_sel_hi:[1,0]
	v_pk_mul_f32 v[40:41], v[40:41], s[28:29] op_sel_hi:[1,0]
	v_pk_mul_f32 v[34:35], v[34:35], s[28:29] op_sel_hi:[1,0]
	v_pk_mul_f32 v[36:37], v[36:37], s[28:29] op_sel_hi:[1,0]
	v_exp_f32_e32 v38, v38
	v_exp_f32_e32 v39, v39
	v_exp_f32_e32 v40, v40
	v_exp_f32_e32 v41, v41
	v_exp_f32_e32 v34, v34
	v_exp_f32_e32 v35, v35
	v_exp_f32_e32 v36, v36
	v_exp_f32_e32 v37, v37
	v_pk_add_f32 v[38:39], v[38:39], s[0:1] op_sel_hi:[1,0]
	v_pk_add_f32 v[40:41], v[40:41], s[0:1] op_sel_hi:[1,0]
	v_pk_add_f32 v[34:35], v[34:35], s[0:1] op_sel_hi:[1,0]
	v_pk_add_f32 v[36:37], v[36:37], s[0:1] op_sel_hi:[1,0]
	v_rcp_f32_e32 v38, v38
	v_rcp_f32_e32 v39, v39
	v_rcp_f32_e32 v40, v40
	v_rcp_f32_e32 v41, v41
	v_rcp_f32_e32 v34, v34
	v_rcp_f32_e32 v35, v35
	v_rcp_f32_e32 v36, v36
	v_rcp_f32_e32 v37, v37
	v_cvt_pk_bf16_f32 v134, v38, v39
	v_cvt_pk_bf16_f32 v135, v40, v41
	v_cvt_pk_bf16_f32 v136, v34, v35
	v_cvt_pk_bf16_f32 v137, v36, v37
	global_store_dwordx4 v166, v[134:137], s[34:35] offset:256 nt
	v_add_u32_e32 v164, 0x424000, v165
	v_pk_mul_f32 v[30:31], v[30:31], v[188:189] op_sel_hi:[1,0]
	v_pk_mul_f32 v[32:33], v[32:33], v[188:189] op_sel_hi:[1,0]
	v_pk_mul_f32 v[26:27], v[26:27], v[188:189] op_sel_hi:[1,0]
	v_pk_mul_f32 v[28:29], v[28:29], v[188:189] op_sel_hi:[1,0]
	v_pk_mul_f32 v[30:31], v[30:31], s[28:29] op_sel_hi:[1,0]
	v_pk_mul_f32 v[32:33], v[32:33], s[28:29] op_sel_hi:[1,0]
	v_pk_mul_f32 v[26:27], v[26:27], s[28:29] op_sel_hi:[1,0]
	v_pk_mul_f32 v[28:29], v[28:29], s[28:29] op_sel_hi:[1,0]
	v_exp_f32_e32 v30, v30
	v_exp_f32_e32 v31, v31
	v_exp_f32_e32 v32, v32
	v_exp_f32_e32 v33, v33
	v_exp_f32_e32 v26, v26
	v_exp_f32_e32 v27, v27
	v_exp_f32_e32 v28, v28
	v_exp_f32_e32 v29, v29
	v_pk_add_f32 v[30:31], v[30:31], s[0:1] op_sel_hi:[1,0]
	v_pk_add_f32 v[32:33], v[32:33], s[0:1] op_sel_hi:[1,0]
	v_pk_add_f32 v[26:27], v[26:27], s[0:1] op_sel_hi:[1,0]
	v_pk_add_f32 v[28:29], v[28:29], s[0:1] op_sel_hi:[1,0]
	v_rcp_f32_e32 v30, v30
	v_rcp_f32_e32 v31, v31
	v_rcp_f32_e32 v32, v32
	v_rcp_f32_e32 v33, v33
	v_rcp_f32_e32 v26, v26
	v_rcp_f32_e32 v27, v27
	v_rcp_f32_e32 v28, v28
	v_rcp_f32_e32 v29, v29
	v_cvt_pk_bf16_f32 v130, v30, v31
	v_cvt_pk_bf16_f32 v131, v32, v33
	v_cvt_pk_bf16_f32 v132, v26, v27
	v_cvt_pk_bf16_f32 v133, v28, v29
	global_store_dwordx4 v164, v[130:133], s[34:35] nt
	v_pk_mul_f32 v[22:23], v[22:23], v[188:189] op_sel_hi:[1,0]
	v_pk_mul_f32 v[24:25], v[24:25], v[188:189] op_sel_hi:[1,0]
	v_pk_mul_f32 v[18:19], v[18:19], v[188:189] op_sel_hi:[1,0]
	v_pk_mul_f32 v[20:21], v[20:21], v[188:189] op_sel_hi:[1,0]
	v_pk_mul_f32 v[22:23], v[22:23], s[28:29] op_sel_hi:[1,0]
	v_pk_mul_f32 v[24:25], v[24:25], s[28:29] op_sel_hi:[1,0]
	v_pk_mul_f32 v[18:19], v[18:19], s[28:29] op_sel_hi:[1,0]
	v_pk_mul_f32 v[20:21], v[20:21], s[28:29] op_sel_hi:[1,0]
	v_exp_f32_e32 v22, v22
	v_exp_f32_e32 v23, v23
	v_exp_f32_e32 v24, v24
	v_exp_f32_e32 v25, v25
	v_exp_f32_e32 v18, v18
	v_exp_f32_e32 v19, v19
	v_exp_f32_e32 v20, v20
	v_exp_f32_e32 v21, v21
	v_pk_add_f32 v[22:23], v[22:23], s[0:1] op_sel_hi:[1,0]
	v_pk_add_f32 v[24:25], v[24:25], s[0:1] op_sel_hi:[1,0]
	v_pk_add_f32 v[18:19], v[18:19], s[0:1] op_sel_hi:[1,0]
	v_pk_add_f32 v[20:21], v[20:21], s[0:1] op_sel_hi:[1,0]
	v_rcp_f32_e32 v22, v22
	v_rcp_f32_e32 v23, v23
	v_rcp_f32_e32 v24, v24
	v_rcp_f32_e32 v25, v25
	v_rcp_f32_e32 v18, v18
	v_rcp_f32_e32 v19, v19
	v_rcp_f32_e32 v20, v20
	v_rcp_f32_e32 v21, v21
	v_cvt_pk_bf16_f32 v134, v22, v23
	v_cvt_pk_bf16_f32 v135, v24, v25
	v_cvt_pk_bf16_f32 v136, v18, v19
	v_cvt_pk_bf16_f32 v137, v20, v21
	global_store_dwordx4 v164, v[134:137], s[34:35] offset:256 nt
	v_add_u32_e32 v166, 0x48e000, v165
	v_pk_mul_f32 v[14:15], v[14:15], v[190:191] op_sel_hi:[1,0]
	v_pk_mul_f32 v[16:17], v[16:17], v[190:191] op_sel_hi:[1,0]
	v_pk_mul_f32 v[10:11], v[10:11], v[190:191] op_sel_hi:[1,0]
	v_pk_mul_f32 v[12:13], v[12:13], v[190:191] op_sel_hi:[1,0]
	v_pk_mul_f32 v[14:15], v[14:15], s[28:29] op_sel_hi:[1,0]
	v_pk_mul_f32 v[16:17], v[16:17], s[28:29] op_sel_hi:[1,0]
	v_pk_mul_f32 v[10:11], v[10:11], s[28:29] op_sel_hi:[1,0]
	v_pk_mul_f32 v[12:13], v[12:13], s[28:29] op_sel_hi:[1,0]
	v_exp_f32_e32 v14, v14
	v_exp_f32_e32 v15, v15
	v_exp_f32_e32 v16, v16
	v_exp_f32_e32 v17, v17
	v_exp_f32_e32 v10, v10
	v_exp_f32_e32 v11, v11
	v_exp_f32_e32 v12, v12
	v_exp_f32_e32 v13, v13
	v_pk_add_f32 v[14:15], v[14:15], s[0:1] op_sel_hi:[1,0]
	v_pk_add_f32 v[16:17], v[16:17], s[0:1] op_sel_hi:[1,0]
	v_pk_add_f32 v[10:11], v[10:11], s[0:1] op_sel_hi:[1,0]
	v_pk_add_f32 v[12:13], v[12:13], s[0:1] op_sel_hi:[1,0]
	v_rcp_f32_e32 v14, v14
	v_rcp_f32_e32 v15, v15
	v_rcp_f32_e32 v16, v16
	v_rcp_f32_e32 v17, v17
	v_rcp_f32_e32 v10, v10
	v_rcp_f32_e32 v11, v11
	v_rcp_f32_e32 v12, v12
	v_rcp_f32_e32 v13, v13
	v_cvt_pk_bf16_f32 v130, v14, v15
	v_cvt_pk_bf16_f32 v131, v16, v17
	v_cvt_pk_bf16_f32 v132, v10, v11
	v_cvt_pk_bf16_f32 v133, v12, v13
	global_store_dwordx4 v166, v[130:133], s[34:35] nt
	v_pk_mul_f32 v[6:7], v[6:7], v[190:191] op_sel_hi:[1,0]
	v_pk_mul_f32 v[8:9], v[8:9], v[190:191] op_sel_hi:[1,0]
	v_pk_mul_f32 v[2:3], v[2:3], v[190:191] op_sel_hi:[1,0]
	v_pk_mul_f32 v[4:5], v[4:5], v[190:191] op_sel_hi:[1,0]
	v_pk_mul_f32 v[6:7], v[6:7], s[28:29] op_sel_hi:[1,0]
	v_pk_mul_f32 v[8:9], v[8:9], s[28:29] op_sel_hi:[1,0]
	v_pk_mul_f32 v[2:3], v[2:3], s[28:29] op_sel_hi:[1,0]
	v_pk_mul_f32 v[4:5], v[4:5], s[28:29] op_sel_hi:[1,0]
	v_exp_f32_e32 v6, v6
	v_exp_f32_e32 v7, v7
	v_exp_f32_e32 v8, v8
	v_exp_f32_e32 v9, v9
	v_exp_f32_e32 v2, v2
	v_exp_f32_e32 v3, v3
	v_exp_f32_e32 v4, v4
	v_exp_f32_e32 v5, v5
	v_pk_add_f32 v[6:7], v[6:7], s[0:1] op_sel_hi:[1,0]
	v_pk_add_f32 v[8:9], v[8:9], s[0:1] op_sel_hi:[1,0]
	v_pk_add_f32 v[2:3], v[2:3], s[0:1] op_sel_hi:[1,0]
	v_pk_add_f32 v[4:5], v[4:5], s[0:1] op_sel_hi:[1,0]
	v_rcp_f32_e32 v6, v6
	v_rcp_f32_e32 v7, v7
	v_rcp_f32_e32 v8, v8
	v_rcp_f32_e32 v9, v9
	v_rcp_f32_e32 v2, v2
	v_rcp_f32_e32 v3, v3
	v_rcp_f32_e32 v4, v4
	v_rcp_f32_e32 v5, v5
	v_cvt_pk_bf16_f32 v134, v6, v7
	v_cvt_pk_bf16_f32 v135, v8, v9
	v_cvt_pk_bf16_f32 v136, v2, v3
	v_cvt_pk_bf16_f32 v137, v4, v5
	global_store_dwordx4 v166, v[134:137], s[34:35] offset:256 nt
	s_branch .Lfe_done
